# K-blocked [K/32][rows][32] f16 layouts for xh and winT: each BK=32 inproj stage is a contiguous run of full 128-B lines
# speedup vs baseline: 1.0770x; 1.0444x over previous
;   __device__ __forceinline__ const float* x() const { return (const float*)(const __attribute__((address_space(1))) float*)kp[0]; }
;   __device__ __forceinline__ const float* ln_g() const { return (const float*)(const __attribute__((address_space(1))) float*)kp[16]; }
;   __device__ __forceinline__ const float* ln_b() const { return (const float*)(const __attribute__((address_space(1))) float*)kp[17]; }
;   __device__ __forceinline__ float* out() const { return (float*)(__attribute__((address_space(1))) float*)kp[18]; }
; __device__ __forceinline__ void ln_rows(const KP& p, int lprev, bool final_) {
;     ...
;   for (int row = gw; row < NTOK; row += nw) {
;     const float4* rp = (const float4*)((lprev < 0 ? p.x() : (const float*)p.u()) + (size_t)row * DM);
;     float4 v[4];
;     float s = 0.f;
; #pragma unroll
;     for (int i = 0; i < 4; ++i) {
;       v[i] = rp[lane + 64 * i];
;       s += v[i].x + v[i].y + v[i].z + v[i].w;
;     }
;     if (lprev >= 0) {
;       float mu = wave_sum(s) * (1.f / DM);
;       float q = 0.f;
; #pragma unroll
;       for (int i = 0; i < 4; ++i) {
;         float a = v[i].x - mu, b = v[i].y - mu, c = v[i].z - mu, d = v[i].w - mu;
;         q += a * a + b * b + c * c + d * d;
;       }
;       float rstd = rsqrtf(wave_sum(q) * (1.f / DM) + 1e-5f);
;       const float4* g4 = (const float4*)(p.ln_g() + lprev * DM);
;       const float4* b4 = (const float4*)(p.ln_b() + lprev * DM);
; #pragma unroll
;       for (int i = 0; i < 4; ++i) {
;         float4 g = g4[lane + 64 * i], bb = b4[lane + 64 * i];
;         v[i].x = (v[i].x - mu) * rstd * g.x + bb.x;
;         v[i].y = (v[i].y - mu) * rstd * g.y + bb.y;
;         v[i].z = (v[i].z - mu) * rstd * g.z + bb.z;
;         v[i].w = (v[i].w - mu) * rstd * g.w + bb.w;
;       }
;     }
;     if (final_) {
;       float4* op = (float4*)(p.out() + (size_t)row * DM);
; #pragma unroll
;       for (int i = 0; i < 4; ++i) op[lane + 64 * i] = v[i];
;     } else {
;       float4* op = (float4*)(p.xr() + (size_t)row * DM);
;       h4* hp = (h4*)(p.xh() + (size_t)row * DM);
; #pragma unroll
;       for (int i = 0; i < 4; ++i) {
;         op[lane + 64 * i] = v[i];
;         h4 hv;
;         hv[0] = (half_t)v[i].x; hv[1] = (half_t)v[i].y; hv[2] = (half_t)v[i].z; hv[3] = (half_t)v[i].w;
;         hp[lane + 64 * i] = hv;
;       }
.LBB0_17:
	s_or_b64 exec, exec, s[6:7]
	v_mov_b32_e32 v1, v224
	v_readlane_b32 s6, v253, 0
	s_lshl_b32 s6, s6, 2
	v_ashrrev_i32_e32 v0, 6, v1
	v_writelane_b32 v253, s6, 3
	v_add_u32_e32 v0, s6, v0
	s_movk_i32 s6, 0x4000
	s_lshl_b32 s70, s46, 2
	v_cmp_gt_i32_e32 vcc, s6, v0
	s_and_saveexec_b64 s[6:7], vcc
	s_cbranch_execz .LBB0_20
	s_load_dwordx2 s[10:11], s[2:3], 0x0
	v_and_b32_e32 v6, 63, v1
	v_and_b32_e32 v33, 7, v6
	v_lshrrev_b32_e32 v34, 3, v6
	v_lshlrev_b32_e32 v33, 3, v33
	v_lshl_or_b32 v33, v34, 20, v33
	v_add_u32_e32 v33, 0x4000000, v33
	v_ashrrev_i32_e32 v1, 31, v0
	v_lshlrev_b64 v[2:3], 11, v[0:1]
	s_ashr_i32 s71, s70, 31
	v_lshlrev_b64 v[4:5], 12, v[0:1]
	v_lshl_or_b32 v2, v6, 3, v2
	s_lshl_b64 s[12:13], s[70:71], 11
	v_lshl_or_b32 v4, v6, 4, v4
	s_lshl_b64 s[14:15], s[70:71], 12
	s_mov_b64 s[16:17], 0
	s_brev_b32 s18, 32
	s_movk_i32 s19, 0x3fff
.LBB0_19:
	s_waitcnt lgkmcnt(0)
	v_lshl_add_u32 v32, v0, 6, v33
	v_lshl_add_u64 v[22:23], s[10:11], 0, v[4:5]
	global_load_dwordx4 v[6:9], v[22:23], off
	global_load_dwordx4 v[10:13], v[22:23], off offset:1024
	global_load_dwordx4 v[14:17], v[22:23], off offset:2048
	global_load_dwordx4 v[18:21], v[22:23], off offset:3072
	v_lshl_add_u64 v[24:25], s[0:1], 0, v[2:3]
	v_add_co_u32_e32 v24, vcc, s18, v24
	v_add_u32_e32 v0, s70, v0
	s_nop 0
	v_addc_co_u32_e32 v25, vcc, 0, v25, vcc
	v_cmp_lt_i32_e32 vcc, s19, v0
	v_lshl_add_u64 v[22:23], s[0:1], 0, v[4:5]
	v_lshl_add_u64 v[2:3], v[2:3], 0, s[12:13]
	v_lshl_add_u64 v[4:5], v[4:5], 0, s[14:15]
	s_or_b64 s[16:17], vcc, s[16:17]
	s_waitcnt vmcnt(3)
	v_cvt_pk_f16_f32 v27, v8, v9
	v_cvt_pk_f16_f32 v26, v6, v7
	s_waitcnt vmcnt(2)
	v_cvt_pk_f16_f32 v29, v12, v13
	v_cvt_pk_f16_f32 v28, v10, v11
	s_waitcnt vmcnt(1)
	v_cvt_pk_f16_f32 v31, v16, v17
	v_cvt_pk_f16_f32 v30, v14, v15
	global_store_dwordx4 v[22:23], v[6:9], off
	s_waitcnt vmcnt(1)
	s_nop 0
	v_cvt_pk_f16_f32 v7, v20, v21
	v_cvt_pk_f16_f32 v6, v18, v19
	global_store_dwordx2 v32, v[26:27], s[0:1]
	global_store_dwordx4 v[22:23], v[10:13], off offset:1024
	v_add_u32_e32 v34, 0x800000, v32
	global_store_dwordx2 v34, v[28:29], s[0:1]
	global_store_dwordx4 v[22:23], v[14:17], off offset:2048
	v_add_u32_e32 v35, 0x1000000, v32
	global_store_dwordx2 v35, v[30:31], s[0:1]
	global_store_dwordx4 v[22:23], v[18:21], off offset:3072
	v_add_u32_e32 v36, 0x1800000, v32
	global_store_dwordx2 v36, v[6:7], s[0:1]
	s_andn2_b64 exec, exec, s[16:17]
	s_cbranch_execnz .LBB0_19

;   __device__ __forceinline__ const float* w_in() const { return (const float*)(const __attribute__((address_space(1))) float*)kp[1]; }
;   __device__ __forceinline__ half_t* winT() const { return (half_t*)(ws() + OFF_winT); }
; template <class CM>
; __device__ __forceinline__ void tconv_tile(const float* __restrict__ src, int lds_, half_t* __restrict__ dst, int ldd,
;                                            int n0, int k0, CM cmap, char* smem) {
;     ...
; #pragma unroll
;   for (int i = 0; i < 2; ++i) {
;     const int idx = tid + 256 * i;
;     const int n = idx >> 3, kc = (idx & 7) * 8;
;     h8 v;
; #pragma unroll
;     for (int j = 0; j < 8; ++j) v[j] = (half_t)t[(kc + j) * 65 + n];
;     *(h8*)&dst[(size_t)(n0 + n) * ldd + k0 + kc] = v;
;   }
; __device__ __forceinline__ void prep_weights(const KP& p, int l, char* smem) {
;     ...
;       tconv_tile(p.w_in() + (size_t)l * DM * NIN, NIN, p.winT(), DM, nt * 64, kt * 64,
.LBB0_22:
	s_or_b64 exec, exec, s[16:17]
	v_and_b32_e32 v6, 63, v8
	v_mul_lo_u32 v7, v9, s39
	v_lshl_add_u32 v6, v6, 2, v7
	s_waitcnt vmcnt(0)
	ds_write_b32 v6, v10
	ds_write_b32 v6, v4 offset:1040
	ds_write_b32 v6, v13 offset:2080
	ds_write_b32 v6, v12 offset:3120
	ds_write_b32 v6, v17 offset:4160
	ds_write_b32 v6, v16 offset:5200
	ds_write_b32 v6, v19 offset:6240
	ds_write_b32 v6, v18 offset:7280
	ds_write_b32 v6, v21 offset:8320
	ds_write_b32 v6, v20 offset:9360
	ds_write_b32 v6, v23 offset:10400
	ds_write_b32 v6, v22 offset:11440
	ds_write_b32 v6, v25 offset:12480
	ds_write_b32 v6, v24 offset:13520
	ds_write_b32 v6, v27 offset:14560
	ds_write_b32 v6, v26 offset:15600
	v_lshlrev_b32_e32 v4, 3, v8
	v_and_b32_e32 v6, 56, v4
	v_mul_u32_u24_e32 v9, 0x104, v6
	v_ashrrev_i32_e32 v22, 3, v8
	s_andn2_b32 s12, s12, 63
	s_lshr_b32 s16, s18, 5
	s_mul_i32 s16, s16, 0x74000
	v_lshl_add_u32 v12, v22, 2, v9
	s_add_u32 s16, s34, s16
	v_add_u32_e32 v10, 0x400, v12
	s_waitcnt lgkmcnt(0)
	s_barrier
	s_addc_u32 s17, s35, 0
	v_lshrrev_b32_e32 v4, 5, v6
	v_and_b32_e32 v20, 31, v6
	v_mul_u32_u24_e32 v4, 0x74000, v4
	v_lshl_add_u32 v4, v20, 1, v4
	ds_read2_b32 v[6:7], v10 offset0:134 offset1:199
	ds_read2_b32 v[10:11], v10 offset0:4 offset1:69
	ds_read2_b32 v[16:17], v12 offset0:130 offset1:195
	ds_read2_b32 v[18:19], v12 offset1:65
	v_lshl_add_u64 v[20:21], s[16:17], 0, v[4:5]
	v_add_u32_e32 v4, 0x100, v8
	v_ashrrev_i32_e32 v4, 3, v4
	s_waitcnt lgkmcnt(3)
	v_cvt_pk_f16_f32 v13, v6, v7
	v_add_u32_e32 v6, s12, v22
	v_lshl_add_u32 v22, v4, 2, v9
	s_waitcnt lgkmcnt(2)
	v_cvt_pk_f16_f32 v12, v10, v11
	s_waitcnt lgkmcnt(1)
	v_cvt_pk_f16_f32 v11, v16, v17
	v_ashrrev_i32_e32 v7, 31, v6
	v_add_u32_e32 v16, 0x400, v22
	s_waitcnt lgkmcnt(0)
	v_cvt_pk_f16_f32 v10, v18, v19
	v_lshlrev_b64 v[6:7], 6, v[6:7]
	ds_read2_b32 v[8:9], v16 offset0:134 offset1:199
	ds_read2_b32 v[16:17], v16 offset0:4 offset1:69
	ds_read2_b32 v[18:19], v22 offset0:130 offset1:195
	ds_read2_b32 v[22:23], v22 offset1:65
	v_lshl_add_u64 v[6:7], v[20:21], 0, v[6:7]
	global_store_dwordx4 v[6:7], v[10:13], off
	s_waitcnt lgkmcnt(3)
	v_cvt_pk_f16_f32 v9, v8, v9
	s_waitcnt lgkmcnt(2)
	v_cvt_pk_f16_f32 v8, v16, v17
	v_add_u32_e32 v10, s12, v4
	v_ashrrev_i32_e32 v11, 31, v10
	v_lshlrev_b64 v[10:11], 6, v[10:11]
	s_waitcnt lgkmcnt(1)
	v_cvt_pk_f16_f32 v7, v18, v19
	s_waitcnt lgkmcnt(0)
	v_cvt_pk_f16_f32 v6, v22, v23
	v_lshl_add_u64 v[10:11], v[20:21], 0, v[10:11]
	global_store_dwordx4 v[10:11], v[6:9], off
	s_barrier

;   __device__ __forceinline__ const float* x() const { return (const float*)(const __attribute__((address_space(1))) float*)kp[0]; }
;   __device__ __forceinline__ const float* b_in() const { return (const float*)(const __attribute__((address_space(1))) float*)kp[2]; }
;   __device__ __forceinline__ half_t* xh() const { return (half_t*)(ws() + OFF_xh); }
;   __device__ __forceinline__ half_t* u() const { return (half_t*)(ws() + OFF_u); }
; template <class LA, class LB, class EP>
; __device__ __forceinline__ void gemm_tile_big(int K, LA loadA, LB loadB, EP epi, char* smem) {
;     ...
;   const int lr = tid >> 3, lc = (tid & 7) * 8;
;   uint4 ra[8], rb[4];
; #pragma unroll
;   for (int i = 0; i < 8; ++i) ra[i] = loadA(lr + 32 * i, lc);
; #pragma unroll
;   for (int i = 0; i < 4; ++i) rb[i] = loadB(lr + 32 * i, lc);
; __device__ __forceinline__ void phase_inproj(const KP& p, int l, char* smem, int* q, int xcc) {
;   const float* bias = p.b_in() + (size_t)l * NIN;
;   xcd_schedule(q, xcc, 128, 32, smem, [&](int grp, int within) __attribute__((always_inline)) {
;     const int mt = (grp & 15) * 4 + (within & 3), nt = (grp >> 4) * 8 + (within >> 2);
;     if (nt >= 58) return;
;     const int m0 = mt * 256, n0 = nt * 128;
;     const half_t* A = p.xh() + (size_t)m0 * DM;
;     const half_t* B = p.winT() + (size_t)n0 * DM;
;     int tidx = threadIdx.x;
;     asm volatile("" : "+v"(tidx));
;     const int lane = tidx & 63, wn = (tidx >> 6) & 1;
;     float bv[2];
; #pragma unroll
;     for (int ni = 0; ni < 2; ++ni) {
;       const int oc = orig_col(n0 + wn * 64 + ni * 32 + (lane & 31));
;       bv[ni] = oc >= 0 ? bias[oc] : 0.f;
;     }
;     half_t* vT = (nt == 53) ? p.vsT() : ((nt == 55) ? p.vwT() : nullptr);
;     gemm_tile_big(
;         DM, [&](int r, int k) { return *(const uint4*)(A + (size_t)r * DM + k); },
;         [&](int r, int k) { return *(const uint4*)(B + (size_t)r * DM + k); },
;         [&](int mi, int ni, int r, int row, int col, float v) {
;           const half_t hv = (half_t)(v + bv[ni]);
;           const int tok = m0 + row;
;           p.u()[(size_t)tok * NU + n0 + col] = hv;
;           if (vT) {
;             const int b = tok >> 13, t = tok & 8191;
;             vT[((size_t)(b * 2 + (col >> 6)) * 64 + (col & 63)) * SEQ + t] = hv;
;           }
;         },
;         smem);
.LBB0_285:
	s_lshl_b32 s2, s42, 2
	s_and_b32 s2, s2, 60
	s_and_b32 s15, s43, 3
	s_or_b32 s14, s2, s15
	v_mov_b32_e32 v194, v224
	s_lshl_b32 s30, s14, 19
	s_lshl_b64 s[2:3], s[18:19], 11
	s_add_u32 s30, s8, s30
	v_ashrrev_i32_e32 v2, 3, v194
	v_lshlrev_b32_e32 v0, 3, v194
	v_and_b32_e32 v20, 56, v0
	v_ashrrev_i32_e32 v3, 31, v2
	s_addc_u32 s31, s44, 0
	v_lshlrev_b32_e32 v0, 1, v20
	v_lshlrev_b64 v[6:7], 11, v[2:3]
	v_lshl_add_u64 v[4:5], s[30:31], 0, v[0:1]
	v_lshl_add_u64 v[10:11], v[6:7], 0, s[20:21]
	v_lshl_add_u64 v[8:9], v[4:5], 0, v[6:7]
	v_lshl_add_u64 v[12:13], v[4:5], 0, v[10:11]
	v_lshl_add_u64 v[12:13], v[6:7], 0, s[80:81]
	v_lshl_add_u64 v[14:15], v[4:5], 0, v[12:13]
	v_lshl_add_u64 v[16:17], v[6:7], 0, s[82:83]
	v_lshl_add_u64 v[18:19], v[4:5], 0, v[16:17]
	v_add_u32_e32 v14, 0x80, v2
	v_ashrrev_i32_e32 v15, 31, v14
	v_lshlrev_b64 v[18:19], 11, v[14:15]
	v_lshl_add_u64 v[4:5], v[4:5], 0, v[18:19]
	v_add_co_u32_e32 v18, vcc, s61, v8
	s_add_u32 s42, s45, s2
	s_nop 0
	v_addc_co_u32_e32 v19, vcc, 0, v9, vcc
	v_add_co_u32_e32 v4, vcc, s64, v8
	s_addc_u32 s43, s46, s3
	s_nop 0
	v_addc_co_u32_e32 v5, vcc, 0, v9, vcc
	v_add_co_u32_e32 v8, vcc, s65, v8
	v_and_b32_e32 v3, 0xfffff9f, v194
	s_nop 0
	v_addc_co_u32_e32 v9, vcc, 0, v9, vcc
	v_lshl_add_u64 v[4:5], s[42:43], 0, v[0:1]
	v_lshl_add_u64 v[8:9], v[4:5], 0, v[6:7]
	v_lshl_add_u64 v[10:11], v[4:5], 0, v[10:11]
	v_lshl_add_u64 v[8:9], v[4:5], 0, v[12:13]
	v_lshl_add_u64 v[4:5], v[4:5], 0, v[16:17]
	v_lshrrev_b32_e32 v4, 1, v194
	v_and_b32_e32 v4, 16, v4
	v_mul_lo_u32 v2, v2, s37
	v_bfe_u32 v247, v194, 6, 1
	v_and_b32_e32 v195, 31, v194
	v_mad_u64_u32 v[178:179], s[30:31], v3, s36, v[4:5]
	v_add_lshl_u32 v196, v2, v20, 1
	v_lshl_add_u64 v[2:3], v[6:7], 0, s[2:3]
	s_add_i32 s2, s52, s53
	v_lshl_or_b32 v249, v247, 6, v195
	v_mad_u64_u32 v[188:189], s[30:31], v14, s36, v[0:1]
	v_or_b32_e32 v0, 0x60, v194
	s_lshl_b32 s2, s2, 19
	v_mad_u64_u32 v[180:181], s[30:31], v0, s36, v[4:5]
	v_mad_u32_u24 v179, v249, s36, v4
	v_lshlrev_b32_e32 v4, 4, v194
	s_and_b32 s2, s2, 0x1e00000
	s_lshl_b32 s3, s15, 19
	v_and_b32_e32 v4, 0x70, v4
	s_or_b32 s2, s2, s3
	v_or_b32_e32 v2, v2, v4
	s_add_u32 s2, s0, s2
	v_lshl_add_u64 v[190:191], s[0:1], 0, v[2:3]
	v_or_b32_e32 v6, v6, v4
	s_addc_u32 s3, s1, 0
	v_mov_b32_e32 v2, 0
	v_add_u32_e32 v198, 0x1200, v188
	v_add_u32_e32 v197, 0x2400, v188
	v_add_u32_e32 v189, 0x3600, v188
	v_add_u32_e32 v0, 0x1200, v179
	v_lshl_add_u64 v[192:193], s[2:3], 0, v[6:7]
	v_mov_b32_e32 v3, v2
	v_mov_b32_e32 v4, v2
	v_mov_b32_e32 v5, v2
	v_mov_b32_e32 v6, v2
	v_mov_b32_e32 v7, v2
	v_mov_b32_e32 v8, v2
	v_mov_b32_e32 v9, v2
	v_mov_b32_e32 v10, v2
	v_mov_b32_e32 v11, v2
	v_mov_b32_e32 v12, v2
	v_mov_b32_e32 v13, v2
	v_mov_b32_e32 v14, v2
	v_mov_b32_e32 v15, v2
	v_mov_b32_e32 v16, v2
	v_mov_b32_e32 v17, v2
	v_mov_b32_e32 v18, v2
	v_mov_b32_e32 v19, v2
	v_mov_b32_e32 v20, v2
	v_mov_b32_e32 v21, v2
	v_mov_b32_e32 v22, v2
	v_mov_b32_e32 v23, v2
	v_mov_b32_e32 v24, v2
	v_mov_b32_e32 v25, v2
	v_mov_b32_e32 v26, v2
	v_mov_b32_e32 v27, v2
	v_mov_b32_e32 v28, v2
	v_mov_b32_e32 v29, v2
	v_mov_b32_e32 v30, v2
	v_mov_b32_e32 v31, v2
	v_mov_b32_e32 v32, v2
	v_mov_b32_e32 v33, v2
	v_mov_b32_e32 v34, v2
	v_mov_b32_e32 v35, v2
	v_mov_b32_e32 v36, v2
	v_mov_b32_e32 v37, v2
	v_mov_b32_e32 v38, v2
	v_mov_b32_e32 v39, v2
	v_mov_b32_e32 v40, v2
	v_mov_b32_e32 v41, v2
	v_mov_b32_e32 v42, v2
	v_mov_b32_e32 v43, v2
	v_mov_b32_e32 v44, v2
	v_mov_b32_e32 v45, v2
	v_mov_b32_e32 v46, v2
	v_mov_b32_e32 v47, v2
	v_mov_b32_e32 v48, v2
	v_mov_b32_e32 v49, v2
	v_mov_b32_e32 v50, v2
	v_mov_b32_e32 v51, v2
	v_mov_b32_e32 v52, v2
	v_mov_b32_e32 v53, v2
	v_mov_b32_e32 v54, v2
	v_mov_b32_e32 v55, v2
	v_mov_b32_e32 v56, v2
	v_mov_b32_e32 v57, v2
	v_mov_b32_e32 v58, v2
	v_mov_b32_e32 v59, v2
	v_mov_b32_e32 v60, v2
	v_mov_b32_e32 v61, v2
	v_mov_b32_e32 v62, v2
	v_mov_b32_e32 v63, v2
	v_mov_b32_e32 v64, v2
	v_mov_b32_e32 v65, v2
	v_mov_b32_e32 v66, v2
	v_mov_b32_e32 v67, v2
	v_mov_b32_e32 v68, v2
	v_mov_b32_e32 v69, v2
	v_mov_b32_e32 v70, v2
	v_mov_b32_e32 v71, v2
	v_mov_b32_e32 v72, v2
	v_mov_b32_e32 v73, v2
	v_mov_b32_e32 v74, v2
	v_mov_b32_e32 v75, v2
	v_mov_b32_e32 v76, v2
	v_mov_b32_e32 v77, v2
	v_mov_b32_e32 v78, v2
	v_mov_b32_e32 v79, v2
	v_mov_b32_e32 v80, v2
	v_mov_b32_e32 v81, v2
	v_mov_b32_e32 v82, v2
	v_mov_b32_e32 v83, v2
	v_mov_b32_e32 v84, v2
	v_mov_b32_e32 v85, v2
	v_mov_b32_e32 v86, v2
	v_mov_b32_e32 v87, v2
	v_mov_b32_e32 v88, v2
	v_mov_b32_e32 v89, v2
	v_mov_b32_e32 v90, v2
	v_mov_b32_e32 v91, v2
	v_mov_b32_e32 v92, v2
	v_mov_b32_e32 v93, v2
	v_mov_b32_e32 v94, v2
	v_mov_b32_e32 v95, v2
	v_mov_b32_e32 v96, v2
	v_mov_b32_e32 v97, v2
	v_mov_b32_e32 v98, v2
	v_mov_b32_e32 v99, v2
	v_mov_b32_e32 v100, v2
	v_mov_b32_e32 v101, v2
	v_mov_b32_e32 v102, v2
	v_mov_b32_e32 v103, v2
	v_mov_b32_e32 v104, v2
	v_mov_b32_e32 v105, v2
	v_mov_b32_e32 v106, v2
	v_mov_b32_e32 v107, v2
	v_mov_b32_e32 v108, v2
	v_mov_b32_e32 v109, v2
	v_mov_b32_e32 v110, v2
	v_mov_b32_e32 v111, v2
	v_mov_b32_e32 v112, v2
	v_mov_b32_e32 v113, v2
	v_mov_b32_e32 v114, v2
	v_mov_b32_e32 v115, v2
	v_mov_b32_e32 v116, v2
	v_mov_b32_e32 v117, v2
	v_mov_b32_e32 v118, v2
	v_mov_b32_e32 v119, v2
	v_mov_b32_e32 v120, v2
	v_mov_b32_e32 v121, v2
	v_mov_b32_e32 v122, v2
	v_mov_b32_e32 v123, v2
	v_mov_b32_e32 v124, v2
	v_mov_b32_e32 v125, v2
	v_mov_b32_e32 v126, v2
	v_mov_b32_e32 v127, v2
	v_mov_b32_e32 v128, v2
	v_mov_b32_e32 v129, v2
	v_lshrrev_b32_e32 v208, 2, v194
	v_and_b32_e32 v209, 3, v194
	v_lshlrev_b32_e32 v210, 11, v208
	v_mul_u32_u24_e32 v196, 0x50, v208
	v_lshl_add_u32 v196, v209, 4, v196
	v_lshlrev_b32_e32 v208, 4, v194
	v_add_u32_e32 v209, 0x1000, v208
	v_add_u32_e32 v210, 0x2000, v208
	v_add_u32_e32 v211, 0x3000, v208
	v_lshrrev_b32_e32 v178, 7, v194
	v_and_b32_e32 v179, 31, v194
	v_lshl_or_b32 v178, v178, 7, v179
	v_mul_u32_u24_e32 v178, 0x50, v178
	v_bfe_u32 v212, v194, 5, 1
	v_lshl_add_u32 v178, v212, 4, v178
	v_bfe_u32 v213, v194, 6, 1
	v_lshl_or_b32 v179, v213, 6, v179
	v_mul_u32_u24_e32 v179, 0x50, v179
	v_lshl_add_u32 v179, v212, 4, v179
	s_lshl_b32 s38, s14, 14
	s_add_u32 s38, s8, s38
	s_addc_u32 s39, s44, 0
	s_lshl_b64 s[2:3], s[18:19], 6
	s_add_u32 s2, s45, s2
	s_addc_u32 s3, s46, s3
	global_load_dwordx4 v[130:133], v208, s[38:39]
	global_load_dwordx4 v[134:137], v209, s[38:39]
	global_load_dwordx4 v[138:141], v210, s[38:39]
	global_load_dwordx4 v[142:145], v211, s[38:39]
	global_load_dwordx4 v[146:149], v208, s[2:3]
	global_load_dwordx4 v[150:153], v209, s[2:3]
	s_add_u32 s38, s38, 0x100000
	s_addc_u32 s39, s39, 0
	s_add_u32 s2, s2, 0x74000
	s_addc_u32 s3, s3, 0
	global_load_dwordx4 v[154:157], v208, s[38:39]
	global_load_dwordx4 v[158:161], v209, s[38:39]
	global_load_dwordx4 v[162:165], v210, s[38:39]
	global_load_dwordx4 v[166:169], v211, s[38:39]
	global_load_dwordx4 v[170:173], v208, s[2:3]
	global_load_dwordx4 v[174:177], v209, s[2:3]
	s_add_u32 s38, s38, 0x100000
	s_addc_u32 s39, s39, 0
	s_add_u32 s2, s2, 0x74000
	s_addc_u32 s3, s3, 0
	s_barrier
; template <class LA, class LB, class EP>
; __device__ __forceinline__ void gemm_tile_big(int K, LA loadA, LB loadB, EP epi, char* smem) {
;     ...
;   for (int kt = 0; kt < nk; ++kt) {
;     __syncthreads();
; #pragma unroll
;     for (int i = 0; i < 8; ++i) *(uint4*)&sA[(lr + 32 * i) * 72 + lc] = ra[i];
; #pragma unroll
;     for (int i = 0; i < 4; ++i) *(uint4*)&sB[(lr + 32 * i) * 72 + lc] = rb[i];
;     __syncthreads();
;     if (kt + 1 < nk) {
;       const int kk = (kt + 1) * 64 + lc;
; #pragma unroll
;       for (int i = 0; i < 8; ++i) ra[i] = loadA(lr + 32 * i, kk);
; #pragma unroll
;       for (int i = 0; i < 4; ++i) rb[i] = loadB(lr + 32 * i, kk);
; __device__ __forceinline__ void phase_inproj(const KP& p, int l, char* smem, int* q, int xcc) {
;     ...
;         DM, [&](int r, int k) { return *(const uint4*)(A + (size_t)r * DM + k); },
;         [&](int r, int k) { return *(const uint4*)(B + (size_t)r * DM + k); },
	s_waitcnt vmcnt(11)
	ds_write_b128 v196, v[130:133]
	s_waitcnt vmcnt(10)
	ds_write_b128 v196, v[134:137] offset:5120
	s_waitcnt vmcnt(9)
	ds_write_b128 v196, v[138:141] offset:10240
	s_waitcnt vmcnt(8)
	ds_write_b128 v196, v[142:145] offset:15360
	s_waitcnt vmcnt(7)
	ds_write_b128 v196, v[146:149] offset:20480
	s_waitcnt vmcnt(6)
	ds_write_b128 v196, v[150:153] offset:25600
	s_waitcnt lgkmcnt(0)
	s_barrier
	s_mov_b32 s30, 0
.Lgp1_loop:
	ds_read_b128 v[238:241], v179 offset:20480
	ds_read_b128 v[242:245], v179 offset:23040
	ds_read_b128 v[200:203], v178
	ds_read_b128 v[204:207], v178 offset:2560
	ds_read_b128 v[214:217], v178 offset:5120
	ds_read_b128 v[218:221], v178 offset:7680
	global_load_dwordx4 v[130:133], v208, s[38:39]
	global_load_dwordx4 v[134:137], v209, s[38:39]
	global_load_dwordx4 v[138:141], v210, s[38:39]
	global_load_dwordx4 v[142:145], v211, s[38:39]
	global_load_dwordx4 v[146:149], v208, s[2:3]
	global_load_dwordx4 v[150:153], v209, s[2:3]
	s_add_u32 s38, s38, 0x100000
	s_addc_u32 s39, s39, 0
	s_add_u32 s2, s2, 0x74000
	s_addc_u32 s3, s3, 0
	ds_read_b128 v[226:229], v179 offset:20512
	ds_read_b128 v[230:233], v179 offset:23072
	s_waitcnt lgkmcnt(5)
	v_mfma_f32_32x32x16_f16 v[114:129], v[200:203], v[238:241], v[114:129]
	v_mfma_f32_32x32x16_f16 v[98:113], v[200:203], v[242:245], v[98:113]
	ds_read_b128 v[200:203], v178 offset:32
	s_waitcnt lgkmcnt(5)
	v_mfma_f32_32x32x16_f16 v[82:97], v[204:207], v[238:241], v[82:97]
	v_mfma_f32_32x32x16_f16 v[66:81], v[204:207], v[242:245], v[66:81]
	ds_read_b128 v[204:207], v178 offset:2592
	s_waitcnt vmcnt(11)
	ds_write_b128 v196, v[154:157] offset:30720
	s_waitcnt lgkmcnt(6)
	v_mfma_f32_32x32x16_f16 v[50:65], v[214:217], v[238:241], v[50:65]
	v_mfma_f32_32x32x16_f16 v[34:49], v[214:217], v[242:245], v[34:49]
	ds_read_b128 v[214:217], v178 offset:5152
	s_waitcnt vmcnt(10)
	ds_write_b128 v196, v[158:161] offset:35840
	s_waitcnt lgkmcnt(7)
	v_mfma_f32_32x32x16_f16 v[18:33], v[218:221], v[238:241], v[18:33]
	v_mfma_f32_32x32x16_f16 v[2:17], v[218:221], v[242:245], v[2:17]
	ds_read_b128 v[218:221], v178 offset:7712
	s_waitcnt vmcnt(9)
	ds_write_b128 v196, v[162:165] offset:40960
	s_waitcnt lgkmcnt(6)
	v_mfma_f32_32x32x16_f16 v[114:129], v[200:203], v[226:229], v[114:129]
	v_mfma_f32_32x32x16_f16 v[98:113], v[200:203], v[230:233], v[98:113]
	s_waitcnt vmcnt(8)
	ds_write_b128 v196, v[166:169] offset:46080
	s_waitcnt lgkmcnt(6)
	v_mfma_f32_32x32x16_f16 v[82:97], v[204:207], v[226:229], v[82:97]
	v_mfma_f32_32x32x16_f16 v[66:81], v[204:207], v[230:233], v[66:81]
	s_waitcnt vmcnt(7)
	ds_write_b128 v196, v[170:173] offset:51200
	s_waitcnt lgkmcnt(5)
	v_mfma_f32_32x32x16_f16 v[50:65], v[214:217], v[226:229], v[50:65]
	v_mfma_f32_32x32x16_f16 v[34:49], v[214:217], v[230:233], v[34:49]
	s_waitcnt vmcnt(6)
	ds_write_b128 v196, v[174:177] offset:56320
	s_waitcnt lgkmcnt(4)
	v_mfma_f32_32x32x16_f16 v[18:33], v[218:221], v[226:229], v[18:33]
	v_mfma_f32_32x32x16_f16 v[2:17], v[218:221], v[230:233], v[2:17]
	s_waitcnt lgkmcnt(0)
	s_barrier
	ds_read_b128 v[238:241], v179 offset:51200
	ds_read_b128 v[242:245], v179 offset:53760
	ds_read_b128 v[200:203], v178 offset:30720
	ds_read_b128 v[204:207], v178 offset:33280
	ds_read_b128 v[214:217], v178 offset:35840
	ds_read_b128 v[218:221], v178 offset:38400
	global_load_dwordx4 v[154:157], v208, s[38:39]
	global_load_dwordx4 v[158:161], v209, s[38:39]
	global_load_dwordx4 v[162:165], v210, s[38:39]
	global_load_dwordx4 v[166:169], v211, s[38:39]
	global_load_dwordx4 v[170:173], v208, s[2:3]
	global_load_dwordx4 v[174:177], v209, s[2:3]
	s_add_u32 s38, s38, 0x100000
	s_addc_u32 s39, s39, 0
	s_add_u32 s2, s2, 0x74000
	s_addc_u32 s3, s3, 0
	ds_read_b128 v[226:229], v179 offset:51232
	ds_read_b128 v[230:233], v179 offset:53792
	s_waitcnt lgkmcnt(5)
	v_mfma_f32_32x32x16_f16 v[114:129], v[200:203], v[238:241], v[114:129]
	v_mfma_f32_32x32x16_f16 v[98:113], v[200:203], v[242:245], v[98:113]
	ds_read_b128 v[200:203], v178 offset:30752
	s_waitcnt lgkmcnt(5)
	v_mfma_f32_32x32x16_f16 v[82:97], v[204:207], v[238:241], v[82:97]
	v_mfma_f32_32x32x16_f16 v[66:81], v[204:207], v[242:245], v[66:81]
	ds_read_b128 v[204:207], v178 offset:33312
	s_waitcnt vmcnt(11)
	ds_write_b128 v196, v[130:133]
	s_waitcnt lgkmcnt(6)
	v_mfma_f32_32x32x16_f16 v[50:65], v[214:217], v[238:241], v[50:65]
	v_mfma_f32_32x32x16_f16 v[34:49], v[214:217], v[242:245], v[34:49]
	ds_read_b128 v[214:217], v178 offset:35872
	s_waitcnt vmcnt(10)
	ds_write_b128 v196, v[134:137] offset:5120
	s_waitcnt lgkmcnt(7)
	v_mfma_f32_32x32x16_f16 v[18:33], v[218:221], v[238:241], v[18:33]
	v_mfma_f32_32x32x16_f16 v[2:17], v[218:221], v[242:245], v[2:17]
	ds_read_b128 v[218:221], v178 offset:38432
	s_waitcnt vmcnt(9)
	ds_write_b128 v196, v[138:141] offset:10240
	s_waitcnt lgkmcnt(6)
	v_mfma_f32_32x32x16_f16 v[114:129], v[200:203], v[226:229], v[114:129]
	v_mfma_f32_32x32x16_f16 v[98:113], v[200:203], v[230:233], v[98:113]
	s_waitcnt vmcnt(8)
	ds_write_b128 v196, v[142:145] offset:15360
	s_waitcnt lgkmcnt(6)
	v_mfma_f32_32x32x16_f16 v[82:97], v[204:207], v[226:229], v[82:97]
	v_mfma_f32_32x32x16_f16 v[66:81], v[204:207], v[230:233], v[66:81]
	s_waitcnt vmcnt(7)
	ds_write_b128 v196, v[146:149] offset:20480
	s_waitcnt lgkmcnt(5)
	v_mfma_f32_32x32x16_f16 v[50:65], v[214:217], v[226:229], v[50:65]
	v_mfma_f32_32x32x16_f16 v[34:49], v[214:217], v[230:233], v[34:49]
	s_waitcnt vmcnt(6)
	ds_write_b128 v196, v[150:153] offset:25600
	s_waitcnt lgkmcnt(4)
	v_mfma_f32_32x32x16_f16 v[18:33], v[218:221], v[226:229], v[18:33]
	v_mfma_f32_32x32x16_f16 v[2:17], v[218:221], v[230:233], v[2:17]
	s_waitcnt lgkmcnt(0)
	s_barrier
; template <class LA, class LB, class EP>
; __device__ __forceinline__ void gemm_tile_big(int K, LA loadA, LB loadB, EP epi, char* smem) {
;     ...
;   for (int kt = 0; kt < nk; ++kt) {
;     __syncthreads();
; #pragma unroll
;     for (int i = 0; i < 8; ++i) *(uint4*)&sA[(lr + 32 * i) * 72 + lc] = ra[i];
; #pragma unroll
;     for (int i = 0; i < 4; ++i) *(uint4*)&sB[(lr + 32 * i) * 72 + lc] = rb[i];
;     __syncthreads();
;     if (kt + 1 < nk) {
;       const int kk = (kt + 1) * 64 + lc;
; #pragma unroll
;       for (int i = 0; i < 8; ++i) ra[i] = loadA(lr + 32 * i, kk);
; #pragma unroll
;       for (int i = 0; i < 4; ++i) rb[i] = loadB(lr + 32 * i, kk);
;     }
; #pragma unroll
;     for (int s = 0; s < 4; ++s) {
;       h8 af[4], bf[2];
; #pragma unroll
;       for (int mi = 0; mi < 4; ++mi)
;         af[mi] = *(const h8*)&sA[(wm * 128 + mi * 32 + (lane & 31)) * 72 + s * 16 + (lane >> 5) * 8];
; #pragma unroll
;       for (int ni = 0; ni < 2; ++ni)
;         bf[ni] = *(const h8*)&sB[(wn * 64 + ni * 32 + (lane & 31)) * 72 + s * 16 + (lane >> 5) * 8];
; #pragma unroll
;       for (int mi = 0; mi < 4; ++mi)
; #pragma unroll
;         for (int ni = 0; ni < 2; ++ni)
;           acc[mi][ni] = __builtin_amdgcn_mfma_f32_32x32x16_f16(af[mi], bf[ni], acc[mi][ni], 0, 0, 0);
;     }
;   }
; __device__ __forceinline__ void phase_inproj(const KP& p, int l, char* smem, int* q, int xcc) {
;     ...
;         [&](int mi, int ni, int r, int row, int col, float v) {
;           const half_t hv = (half_t)(v + bv[ni]);
	s_add_i32 s30, s30, 1
	s_cmp_lt_u32 s30, 15
	s_cbranch_scc1 .Lgp1_loop
	ds_read_b128 v[238:241], v179 offset:20480
	ds_read_b128 v[242:245], v179 offset:23040
	ds_read_b128 v[200:203], v178
	ds_read_b128 v[204:207], v178 offset:2560
	ds_read_b128 v[214:217], v178 offset:5120
	ds_read_b128 v[218:221], v178 offset:7680
	ds_read_b128 v[226:229], v179 offset:20512
	ds_read_b128 v[230:233], v179 offset:23072
	s_waitcnt lgkmcnt(5)
	v_mfma_f32_32x32x16_f16 v[114:129], v[200:203], v[238:241], v[114:129]
	v_mfma_f32_32x32x16_f16 v[98:113], v[200:203], v[242:245], v[98:113]
	ds_read_b128 v[200:203], v178 offset:32
	s_waitcnt lgkmcnt(5)
	v_mfma_f32_32x32x16_f16 v[82:97], v[204:207], v[238:241], v[82:97]
	v_mfma_f32_32x32x16_f16 v[66:81], v[204:207], v[242:245], v[66:81]
	ds_read_b128 v[204:207], v178 offset:2592
	s_waitcnt vmcnt(5)
	ds_write_b128 v196, v[154:157] offset:30720
	s_waitcnt lgkmcnt(6)
	v_mfma_f32_32x32x16_f16 v[50:65], v[214:217], v[238:241], v[50:65]
	v_mfma_f32_32x32x16_f16 v[34:49], v[214:217], v[242:245], v[34:49]
	ds_read_b128 v[214:217], v178 offset:5152
	s_waitcnt vmcnt(4)
	ds_write_b128 v196, v[158:161] offset:35840
	s_waitcnt lgkmcnt(7)
	v_mfma_f32_32x32x16_f16 v[18:33], v[218:221], v[238:241], v[18:33]
	v_mfma_f32_32x32x16_f16 v[2:17], v[218:221], v[242:245], v[2:17]
	ds_read_b128 v[218:221], v178 offset:7712
	s_waitcnt vmcnt(3)
	ds_write_b128 v196, v[162:165] offset:40960
	s_waitcnt lgkmcnt(6)
	v_mfma_f32_32x32x16_f16 v[114:129], v[200:203], v[226:229], v[114:129]
	v_mfma_f32_32x32x16_f16 v[98:113], v[200:203], v[230:233], v[98:113]
	s_waitcnt vmcnt(2)
	ds_write_b128 v196, v[166:169] offset:46080
	s_waitcnt lgkmcnt(6)
	v_mfma_f32_32x32x16_f16 v[82:97], v[204:207], v[226:229], v[82:97]
	v_mfma_f32_32x32x16_f16 v[66:81], v[204:207], v[230:233], v[66:81]
	s_waitcnt vmcnt(1)
	ds_write_b128 v196, v[170:173] offset:51200
	s_waitcnt lgkmcnt(5)
	v_mfma_f32_32x32x16_f16 v[50:65], v[214:217], v[226:229], v[50:65]
	v_mfma_f32_32x32x16_f16 v[34:49], v[214:217], v[230:233], v[34:49]
	s_waitcnt vmcnt(0)
	ds_write_b128 v196, v[174:177] offset:56320
	s_waitcnt lgkmcnt(4)
	v_mfma_f32_32x32x16_f16 v[18:33], v[218:221], v[226:229], v[18:33]
	v_mfma_f32_32x32x16_f16 v[2:17], v[218:221], v[230:233], v[2:17]
	s_waitcnt lgkmcnt(0)
	s_barrier
	ds_read_b128 v[238:241], v179 offset:51200
	ds_read_b128 v[242:245], v179 offset:53760
	ds_read_b128 v[200:203], v178 offset:30720
	ds_read_b128 v[204:207], v178 offset:33280
	ds_read_b128 v[214:217], v178 offset:35840
	ds_read_b128 v[218:221], v178 offset:38400
	ds_read_b128 v[226:229], v179 offset:51232
	ds_read_b128 v[230:233], v179 offset:53792
	s_waitcnt lgkmcnt(5)
	v_mfma_f32_32x32x16_f16 v[114:129], v[200:203], v[238:241], v[114:129]
	v_mfma_f32_32x32x16_f16 v[98:113], v[200:203], v[242:245], v[98:113]
	ds_read_b128 v[200:203], v178 offset:30752
	s_waitcnt lgkmcnt(5)
	v_mfma_f32_32x32x16_f16 v[82:97], v[204:207], v[238:241], v[82:97]
	v_mfma_f32_32x32x16_f16 v[66:81], v[204:207], v[242:245], v[66:81]
	ds_read_b128 v[204:207], v178 offset:33312
	s_waitcnt lgkmcnt(5)
	v_mfma_f32_32x32x16_f16 v[50:65], v[214:217], v[238:241], v[50:65]
	v_mfma_f32_32x32x16_f16 v[34:49], v[214:217], v[242:245], v[34:49]
	ds_read_b128 v[214:217], v178 offset:35872
	s_waitcnt lgkmcnt(5)
	v_mfma_f32_32x32x16_f16 v[18:33], v[218:221], v[238:241], v[18:33]
	v_mfma_f32_32x32x16_f16 v[2:17], v[218:221], v[242:245], v[2:17]
	ds_read_b128 v[218:221], v178 offset:38432
	s_waitcnt lgkmcnt(3)
	v_mfma_f32_32x32x16_f16 v[114:129], v[200:203], v[226:229], v[114:129]
	v_mfma_f32_32x32x16_f16 v[98:113], v[200:203], v[230:233], v[98:113]
	s_waitcnt lgkmcnt(2)
	v_mfma_f32_32x32x16_f16 v[82:97], v[204:207], v[226:229], v[82:97]
	v_mfma_f32_32x32x16_f16 v[66:81], v[204:207], v[230:233], v[66:81]
	s_waitcnt lgkmcnt(1)
	v_mfma_f32_32x32x16_f16 v[50:65], v[214:217], v[226:229], v[50:65]
	v_mfma_f32_32x32x16_f16 v[34:49], v[214:217], v[230:233], v[34:49]
	s_waitcnt lgkmcnt(0)
	v_mfma_f32_32x32x16_f16 v[18:33], v[218:221], v[226:229], v[18:33]
	v_mfma_f32_32x32x16_f16 v[2:17], v[218:221], v[230:233], v[2:17]
	s_waitcnt lgkmcnt(0)
	v_mov_b32_e32 v226, 1
	v_mov_b32_e32 v227, 0x11fe0
	v_mov_b32_e32 v228, 0x11fe4
	v_mov_b32_e32 v229, 0x100
	v_mov_b32_e32 v230, 2
	v_mov_b32_e32 v231, 0x3727c5ac
	v_mov_b32_e32 v232, 0x11fa0
	v_mov_b32_e32 v233, 0x80000
	v_mov_b32_e32 v238, 0x4000
	v_mov_b32_e32 v239, 0x4400
	v_mov_b32_e32 v240, 0x4800
	v_mov_b32_e32 v241, 0x4c00
	v_mov_b32_e32 v242, 0xf149f2ca
	v_mov_b32_e32 v243, 0x200
	v_mov_b32_e32 v244, 0x400
	v_mov_b32_e32 v245, 0x600
	s_nop 15
	s_lshl_b32 s14, s14, 8
	s_lshl_b64 s[2:3], s[18:19], 1
	s_add_u32 s18, s47, s2
	s_addc_u32 s19, s48, s3
	s_mul_i32 s2, s14, 0x3a00
	s_add_u32 s18, s18, s2
	s_addc_u32 s19, s19, 0
	v_lshrrev_b32_e32 v130, 7, v224
	v_lshlrev_b32_e32 v130, 5, v130
	v_bfe_u32 v131, v224, 5, 1
	v_add_u32_e32 v130, v130, v131
	v_mul_u32_u24_e32 v132, 0xe800, v130
	v_bfe_u32 v131, v224, 6, 1
	v_and_b32_e32 v133, 31, v224
	v_lshl_or_b32 v134, v131, 6, v133
	v_lshl_add_u32 v132, v134, 1, v132
	v_add_f32_e32 v114, v246, v114
	v_cvt_f16_f32_e32 v114, v114
	v_add_f32_e32 v115, v246, v115
	v_cvt_f16_f32_e32 v115, v115
	v_add_f32_e32 v116, v246, v116
	v_cvt_f16_f32_e32 v116, v116
	v_add_f32_e32 v117, v246, v117
	v_cvt_f16_f32_e32 v117, v117
	v_add_f32_e32 v118, v246, v118
	v_cvt_f16_f32_e32 v118, v118
	v_add_f32_e32 v119, v246, v119
	v_cvt_f16_f32_e32 v119, v119
	v_add_f32_e32 v120, v246, v120
	v_cvt_f16_f32_e32 v120, v120
	v_add_f32_e32 v121, v246, v121
	v_cvt_f16_f32_e32 v121, v121
	v_add_f32_e32 v122, v246, v122
	v_cvt_f16_f32_e32 v122, v122
	v_add_f32_e32 v123, v246, v123
	v_cvt_f16_f32_e32 v123, v123
; __device__ __forceinline__ void phase_inproj(const KP& p, int l, char* smem, int* q, int xcc) {
;     ...
;         [&](int mi, int ni, int r, int row, int col, float v) {
;           const half_t hv = (half_t)(v + bv[ni]);
	v_add_f32_e32 v124, v246, v124
	v_cvt_f16_f32_e32 v124, v124
	v_add_f32_e32 v125, v246, v125
	v_cvt_f16_f32_e32 v125, v125
	v_add_f32_e32 v126, v246, v126
	v_cvt_f16_f32_e32 v126, v126
	v_add_f32_e32 v127, v246, v127
	v_cvt_f16_f32_e32 v127, v127
	v_add_f32_e32 v128, v246, v128
	v_cvt_f16_f32_e32 v128, v128
	v_add_f32_e32 v129, v246, v129
	v_cvt_f16_f32_e32 v129, v129
	v_add_f32_e32 v98, v187, v98
	v_cvt_f16_f32_e32 v98, v98
	v_add_f32_e32 v99, v187, v99
	v_cvt_f16_f32_e32 v99, v99
	v_add_f32_e32 v100, v187, v100
	v_cvt_f16_f32_e32 v100, v100
	v_add_f32_e32 v101, v187, v101
	v_cvt_f16_f32_e32 v101, v101
	v_add_f32_e32 v102, v187, v102
	v_cvt_f16_f32_e32 v102, v102
	v_add_f32_e32 v103, v187, v103
	v_cvt_f16_f32_e32 v103, v103
	v_add_f32_e32 v104, v187, v104
	v_cvt_f16_f32_e32 v104, v104
	v_add_f32_e32 v105, v187, v105
	v_cvt_f16_f32_e32 v105, v105
	v_add_f32_e32 v106, v187, v106
	v_cvt_f16_f32_e32 v106, v106
	v_add_f32_e32 v107, v187, v107
	v_cvt_f16_f32_e32 v107, v107
	v_add_f32_e32 v108, v187, v108
	v_cvt_f16_f32_e32 v108, v108
	v_add_f32_e32 v109, v187, v109
	v_cvt_f16_f32_e32 v109, v109
	v_add_f32_e32 v110, v187, v110
	v_cvt_f16_f32_e32 v110, v110
	v_add_f32_e32 v111, v187, v111
	v_cvt_f16_f32_e32 v111, v111
	v_add_f32_e32 v112, v187, v112
	v_cvt_f16_f32_e32 v112, v112
	v_add_f32_e32 v113, v187, v113
	v_cvt_f16_f32_e32 v113, v113
	v_add_f32_e32 v82, v246, v82
	v_cvt_f16_f32_e32 v82, v82
	v_add_f32_e32 v83, v246, v83
	v_cvt_f16_f32_e32 v83, v83
	v_add_f32_e32 v84, v246, v84
	v_cvt_f16_f32_e32 v84, v84
	v_add_f32_e32 v85, v246, v85
	v_cvt_f16_f32_e32 v85, v85
	v_add_f32_e32 v86, v246, v86
	v_cvt_f16_f32_e32 v86, v86
	v_add_f32_e32 v87, v246, v87
	v_cvt_f16_f32_e32 v87, v87
	v_add_f32_e32 v88, v246, v88
	v_cvt_f16_f32_e32 v88, v88
	v_add_f32_e32 v89, v246, v89
	v_cvt_f16_f32_e32 v89, v89
	v_add_f32_e32 v90, v246, v90
	v_cvt_f16_f32_e32 v90, v90
	v_add_f32_e32 v91, v246, v91
	v_cvt_f16_f32_e32 v91, v91
	v_add_f32_e32 v92, v246, v92
	v_cvt_f16_f32_e32 v92, v92
	v_add_f32_e32 v93, v246, v93
	v_cvt_f16_f32_e32 v93, v93
	v_add_f32_e32 v94, v246, v94
	v_cvt_f16_f32_e32 v94, v94
	v_add_f32_e32 v95, v246, v95
	v_cvt_f16_f32_e32 v95, v95
	v_add_f32_e32 v96, v246, v96
	v_cvt_f16_f32_e32 v96, v96
	v_add_f32_e32 v97, v246, v97
	v_cvt_f16_f32_e32 v97, v97
	v_add_f32_e32 v66, v187, v66
	v_cvt_f16_f32_e32 v66, v66
	v_add_f32_e32 v67, v187, v67
	v_cvt_f16_f32_e32 v67, v67
	v_add_f32_e32 v68, v187, v68
	v_cvt_f16_f32_e32 v68, v68
	v_add_f32_e32 v69, v187, v69
	v_cvt_f16_f32_e32 v69, v69
	v_add_f32_e32 v70, v187, v70
	v_cvt_f16_f32_e32 v70, v70
	v_add_f32_e32 v71, v187, v71
	v_cvt_f16_f32_e32 v71, v71
	v_add_f32_e32 v72, v187, v72
	v_cvt_f16_f32_e32 v72, v72
	v_add_f32_e32 v73, v187, v73
	v_cvt_f16_f32_e32 v73, v73
	v_add_f32_e32 v74, v187, v74
	v_cvt_f16_f32_e32 v74, v74
	v_add_f32_e32 v75, v187, v75
	v_cvt_f16_f32_e32 v75, v75
	v_add_f32_e32 v76, v187, v76
	v_cvt_f16_f32_e32 v76, v76
	v_add_f32_e32 v77, v187, v77
	v_cvt_f16_f32_e32 v77, v77
	v_add_f32_e32 v78, v187, v78
	v_cvt_f16_f32_e32 v78, v78
	v_add_f32_e32 v79, v187, v79
	v_cvt_f16_f32_e32 v79, v79
	v_add_f32_e32 v80, v187, v80
	v_cvt_f16_f32_e32 v80, v80
	v_add_f32_e32 v81, v187, v81
	v_cvt_f16_f32_e32 v81, v81
	v_add_f32_e32 v50, v246, v50
	v_cvt_f16_f32_e32 v50, v50
	v_add_f32_e32 v51, v246, v51
	v_cvt_f16_f32_e32 v51, v51
	v_add_f32_e32 v52, v246, v52
	v_cvt_f16_f32_e32 v52, v52
	v_add_f32_e32 v53, v246, v53
	v_cvt_f16_f32_e32 v53, v53
	v_add_f32_e32 v54, v246, v54
	v_cvt_f16_f32_e32 v54, v54
	v_add_f32_e32 v55, v246, v55
	v_cvt_f16_f32_e32 v55, v55
	v_add_f32_e32 v56, v246, v56
	v_cvt_f16_f32_e32 v56, v56
	v_add_f32_e32 v57, v246, v57
	v_cvt_f16_f32_e32 v57, v57
	v_add_f32_e32 v58, v246, v58
	v_cvt_f16_f32_e32 v58, v58
	v_add_f32_e32 v59, v246, v59
	v_cvt_f16_f32_e32 v59, v59
	v_add_f32_e32 v60, v246, v60
	v_cvt_f16_f32_e32 v60, v60
	v_add_f32_e32 v61, v246, v61
	v_cvt_f16_f32_e32 v61, v61
	v_add_f32_e32 v62, v246, v62
	v_cvt_f16_f32_e32 v62, v62
	v_add_f32_e32 v63, v246, v63
	v_cvt_f16_f32_e32 v63, v63
	v_add_f32_e32 v64, v246, v64
	v_cvt_f16_f32_e32 v64, v64
	v_add_f32_e32 v65, v246, v65
	v_cvt_f16_f32_e32 v65, v65
	v_add_f32_e32 v34, v187, v34
	v_cvt_f16_f32_e32 v34, v34
	v_add_f32_e32 v35, v187, v35
	v_cvt_f16_f32_e32 v35, v35
	v_add_f32_e32 v36, v187, v36
	v_cvt_f16_f32_e32 v36, v36
	v_add_f32_e32 v37, v187, v37
	v_cvt_f16_f32_e32 v37, v37
	v_add_f32_e32 v38, v187, v38
	v_cvt_f16_f32_e32 v38, v38
	v_add_f32_e32 v39, v187, v39
	v_cvt_f16_f32_e32 v39, v39
	v_add_f32_e32 v40, v187, v40
	v_cvt_f16_f32_e32 v40, v40
	v_add_f32_e32 v41, v187, v41
	v_cvt_f16_f32_e32 v41, v41
	v_add_f32_e32 v42, v187, v42
	v_cvt_f16_f32_e32 v42, v42
	v_add_f32_e32 v43, v187, v43
	v_cvt_f16_f32_e32 v43, v43
	v_add_f32_e32 v44, v187, v44
	v_cvt_f16_f32_e32 v44, v44
	v_add_f32_e32 v45, v187, v45
	v_cvt_f16_f32_e32 v45, v45
	v_add_f32_e32 v46, v187, v46
	v_cvt_f16_f32_e32 v46, v46
	v_add_f32_e32 v47, v187, v47
	v_cvt_f16_f32_e32 v47, v47
	v_add_f32_e32 v48, v187, v48
	v_cvt_f16_f32_e32 v48, v48
	v_add_f32_e32 v49, v187, v49
	v_cvt_f16_f32_e32 v49, v49
	v_add_f32_e32 v18, v246, v18
	v_cvt_f16_f32_e32 v18, v18
	v_add_f32_e32 v19, v246, v19
	v_cvt_f16_f32_e32 v19, v19
	v_add_f32_e32 v20, v246, v20
	v_cvt_f16_f32_e32 v20, v20
	v_add_f32_e32 v21, v246, v21
	v_cvt_f16_f32_e32 v21, v21
	v_add_f32_e32 v22, v246, v22
	v_cvt_f16_f32_e32 v22, v22
	v_add_f32_e32 v23, v246, v23
	v_cvt_f16_f32_e32 v23, v23
	v_add_f32_e32 v24, v246, v24
	v_cvt_f16_f32_e32 v24, v24
	v_add_f32_e32 v25, v246, v25
	v_cvt_f16_f32_e32 v25, v25
	v_add_f32_e32 v26, v246, v26
	v_cvt_f16_f32_e32 v26, v26
	v_add_f32_e32 v27, v246, v27
	v_cvt_f16_f32_e32 v27, v27
;   __device__ __forceinline__ half_t* u() const { return (half_t*)(ws() + OFF_u); }
; __device__ __forceinline__ void phase_inproj(const KP& p, int l, char* smem, int* q, int xcc) {
;     ...
;         [&](int mi, int ni, int r, int row, int col, float v) {
;           const half_t hv = (half_t)(v + bv[ni]);
;           const int tok = m0 + row;
;           p.u()[(size_t)tok * NU + n0 + col] = hv;
	v_add_f32_e32 v28, v246, v28
	v_cvt_f16_f32_e32 v28, v28
	v_add_f32_e32 v29, v246, v29
	v_cvt_f16_f32_e32 v29, v29
	v_add_f32_e32 v30, v246, v30
	v_cvt_f16_f32_e32 v30, v30
	v_add_f32_e32 v31, v246, v31
	v_cvt_f16_f32_e32 v31, v31
	v_add_f32_e32 v32, v246, v32
	v_cvt_f16_f32_e32 v32, v32
	v_add_f32_e32 v33, v246, v33
	v_cvt_f16_f32_e32 v33, v33
	v_add_f32_e32 v2, v187, v2
	v_cvt_f16_f32_e32 v2, v2
	v_add_f32_e32 v3, v187, v3
	v_cvt_f16_f32_e32 v3, v3
	v_add_f32_e32 v4, v187, v4
	v_cvt_f16_f32_e32 v4, v4
	v_add_f32_e32 v5, v187, v5
	v_cvt_f16_f32_e32 v5, v5
	v_add_f32_e32 v6, v187, v6
	v_cvt_f16_f32_e32 v6, v6
	v_add_f32_e32 v7, v187, v7
	v_cvt_f16_f32_e32 v7, v7
	v_add_f32_e32 v8, v187, v8
	v_cvt_f16_f32_e32 v8, v8
	v_add_f32_e32 v9, v187, v9
	v_cvt_f16_f32_e32 v9, v9
	v_add_f32_e32 v10, v187, v10
	v_cvt_f16_f32_e32 v10, v10
	v_add_f32_e32 v11, v187, v11
	v_cvt_f16_f32_e32 v11, v11
	v_add_f32_e32 v12, v187, v12
	v_cvt_f16_f32_e32 v12, v12
	v_add_f32_e32 v13, v187, v13
	v_cvt_f16_f32_e32 v13, v13
	v_add_f32_e32 v14, v187, v14
	v_cvt_f16_f32_e32 v14, v14
	v_add_f32_e32 v15, v187, v15
	v_cvt_f16_f32_e32 v15, v15
	v_add_f32_e32 v16, v187, v16
	v_cvt_f16_f32_e32 v16, v16
	v_add_f32_e32 v17, v187, v17
	v_cvt_f16_f32_e32 v17, v17
	s_add_u32 s2, s18, 0x0
	s_addc_u32 s3, s19, 0
	global_store_short v132, v114, s[2:3]
	global_store_short v132, v98, s[2:3] offset:64
	s_add_u32 s2, s18, 0x3a00
	s_addc_u32 s3, s19, 0
	global_store_short v132, v115, s[2:3]
	global_store_short v132, v99, s[2:3] offset:64
	s_add_u32 s2, s18, 0x7400
	s_addc_u32 s3, s19, 0
	global_store_short v132, v116, s[2:3]
	global_store_short v132, v100, s[2:3] offset:64
	s_add_u32 s2, s18, 0xae00
	s_addc_u32 s3, s19, 0
	global_store_short v132, v117, s[2:3]
	global_store_short v132, v101, s[2:3] offset:64
	s_add_u32 s2, s18, 0x1d000
	s_addc_u32 s3, s19, 0
	global_store_short v132, v118, s[2:3]
	global_store_short v132, v102, s[2:3] offset:64
	s_add_u32 s2, s18, 0x20a00
	s_addc_u32 s3, s19, 0
	global_store_short v132, v119, s[2:3]
	global_store_short v132, v103, s[2:3] offset:64
	s_add_u32 s2, s18, 0x24400
	s_addc_u32 s3, s19, 0
	global_store_short v132, v120, s[2:3]
	global_store_short v132, v104, s[2:3] offset:64
	s_add_u32 s2, s18, 0x27e00
	s_addc_u32 s3, s19, 0
	global_store_short v132, v121, s[2:3]
	global_store_short v132, v105, s[2:3] offset:64
	s_add_u32 s2, s18, 0x3a000
	s_addc_u32 s3, s19, 0
	global_store_short v132, v122, s[2:3]
	global_store_short v132, v106, s[2:3] offset:64
	s_add_u32 s2, s18, 0x3da00
	s_addc_u32 s3, s19, 0
	global_store_short v132, v123, s[2:3]
	global_store_short v132, v107, s[2:3] offset:64
	s_add_u32 s2, s18, 0x41400
	s_addc_u32 s3, s19, 0
	global_store_short v132, v124, s[2:3]
	global_store_short v132, v108, s[2:3] offset:64
	s_add_u32 s2, s18, 0x44e00
	s_addc_u32 s3, s19, 0
	global_store_short v132, v125, s[2:3]
	global_store_short v132, v109, s[2:3] offset:64
	s_add_u32 s2, s18, 0x57000
	s_addc_u32 s3, s19, 0
	global_store_short v132, v126, s[2:3]
	global_store_short v132, v110, s[2:3] offset:64
	s_add_u32 s2, s18, 0x5aa00
	s_addc_u32 s3, s19, 0
	global_store_short v132, v127, s[2:3]
	global_store_short v132, v111, s[2:3] offset:64
	s_add_u32 s2, s18, 0x5e400
	s_addc_u32 s3, s19, 0
	global_store_short v132, v128, s[2:3]
	global_store_short v132, v112, s[2:3] offset:64
	s_add_u32 s2, s18, 0x61e00
	s_addc_u32 s3, s19, 0
	global_store_short v132, v129, s[2:3]
	global_store_short v132, v113, s[2:3] offset:64
	s_add_u32 s2, s18, 0x74000
	s_addc_u32 s3, s19, 0
	global_store_short v132, v82, s[2:3]
	global_store_short v132, v66, s[2:3] offset:64
	s_add_u32 s2, s18, 0x77a00
	s_addc_u32 s3, s19, 0
	global_store_short v132, v83, s[2:3]
	global_store_short v132, v67, s[2:3] offset:64
	s_add_u32 s2, s18, 0x7b400
	s_addc_u32 s3, s19, 0
	global_store_short v132, v84, s[2:3]
	global_store_short v132, v68, s[2:3] offset:64
	s_add_u32 s2, s18, 0x7ee00
	s_addc_u32 s3, s19, 0
	global_store_short v132, v85, s[2:3]
	global_store_short v132, v69, s[2:3] offset:64
	s_add_u32 s2, s18, 0x91000
	s_addc_u32 s3, s19, 0
	global_store_short v132, v86, s[2:3]
	global_store_short v132, v70, s[2:3] offset:64
	s_add_u32 s2, s18, 0x94a00
	s_addc_u32 s3, s19, 0
	global_store_short v132, v87, s[2:3]
	global_store_short v132, v71, s[2:3] offset:64
	s_add_u32 s2, s18, 0x98400
	s_addc_u32 s3, s19, 0
	global_store_short v132, v88, s[2:3]
	global_store_short v132, v72, s[2:3] offset:64
	s_add_u32 s2, s18, 0x9be00
	s_addc_u32 s3, s19, 0
	global_store_short v132, v89, s[2:3]
	global_store_short v132, v73, s[2:3] offset:64
	s_add_u32 s2, s18, 0xae000
	s_addc_u32 s3, s19, 0
	global_store_short v132, v90, s[2:3]
	global_store_short v132, v74, s[2:3] offset:64
	s_add_u32 s2, s18, 0xb1a00
	s_addc_u32 s3, s19, 0
	global_store_short v132, v91, s[2:3]
	global_store_short v132, v75, s[2:3] offset:64
	s_add_u32 s2, s18, 0xb5400
	s_addc_u32 s3, s19, 0
	global_store_short v132, v92, s[2:3]
	global_store_short v132, v76, s[2:3] offset:64
	s_add_u32 s2, s18, 0xb8e00
	s_addc_u32 s3, s19, 0
	global_store_short v132, v93, s[2:3]
	global_store_short v132, v77, s[2:3] offset:64
	s_add_u32 s2, s18, 0xcb000
	s_addc_u32 s3, s19, 0
	global_store_short v132, v94, s[2:3]
	global_store_short v132, v78, s[2:3] offset:64
	s_add_u32 s2, s18, 0xcea00
	s_addc_u32 s3, s19, 0
	global_store_short v132, v95, s[2:3]
	global_store_short v132, v79, s[2:3] offset:64
	s_add_u32 s2, s18, 0xd2400
	s_addc_u32 s3, s19, 0
	global_store_short v132, v96, s[2:3]
	global_store_short v132, v80, s[2:3] offset:64
	s_add_u32 s2, s18, 0xd5e00
	s_addc_u32 s3, s19, 0
	global_store_short v132, v97, s[2:3]
	global_store_short v132, v81, s[2:3] offset:64
;   __device__ __forceinline__ half_t* u() const { return (half_t*)(ws() + OFF_u); }
; __device__ __forceinline__ void phase_inproj(const KP& p, int l, char* smem, int* q, int xcc) {
;     ...
;           const int tok = m0 + row;
;           p.u()[(size_t)tok * NU + n0 + col] = hv;
;           if (vT) {
	s_add_u32 s2, s18, 0xe8000
	s_addc_u32 s3, s19, 0
	global_store_short v132, v50, s[2:3]
	global_store_short v132, v34, s[2:3] offset:64
	s_add_u32 s2, s18, 0xeba00
	s_addc_u32 s3, s19, 0
	global_store_short v132, v51, s[2:3]
	global_store_short v132, v35, s[2:3] offset:64
	s_add_u32 s2, s18, 0xef400
	s_addc_u32 s3, s19, 0
	global_store_short v132, v52, s[2:3]
	global_store_short v132, v36, s[2:3] offset:64
	s_add_u32 s2, s18, 0xf2e00
	s_addc_u32 s3, s19, 0
	global_store_short v132, v53, s[2:3]
	global_store_short v132, v37, s[2:3] offset:64
	s_add_u32 s2, s18, 0x105000
	s_addc_u32 s3, s19, 0
	global_store_short v132, v54, s[2:3]
	global_store_short v132, v38, s[2:3] offset:64
	s_add_u32 s2, s18, 0x108a00
	s_addc_u32 s3, s19, 0
	global_store_short v132, v55, s[2:3]
	global_store_short v132, v39, s[2:3] offset:64
	s_add_u32 s2, s18, 0x10c400
	s_addc_u32 s3, s19, 0
	global_store_short v132, v56, s[2:3]
	global_store_short v132, v40, s[2:3] offset:64
	s_add_u32 s2, s18, 0x10fe00
	s_addc_u32 s3, s19, 0
	global_store_short v132, v57, s[2:3]
	global_store_short v132, v41, s[2:3] offset:64
	s_add_u32 s2, s18, 0x122000
	s_addc_u32 s3, s19, 0
	global_store_short v132, v58, s[2:3]
	global_store_short v132, v42, s[2:3] offset:64
	s_add_u32 s2, s18, 0x125a00
	s_addc_u32 s3, s19, 0
	global_store_short v132, v59, s[2:3]
	global_store_short v132, v43, s[2:3] offset:64
	s_add_u32 s2, s18, 0x129400
	s_addc_u32 s3, s19, 0
	global_store_short v132, v60, s[2:3]
	global_store_short v132, v44, s[2:3] offset:64
	s_add_u32 s2, s18, 0x12ce00
	s_addc_u32 s3, s19, 0
	global_store_short v132, v61, s[2:3]
	global_store_short v132, v45, s[2:3] offset:64
	s_add_u32 s2, s18, 0x13f000
	s_addc_u32 s3, s19, 0
	global_store_short v132, v62, s[2:3]
	global_store_short v132, v46, s[2:3] offset:64
	s_add_u32 s2, s18, 0x142a00
	s_addc_u32 s3, s19, 0
	global_store_short v132, v63, s[2:3]
	global_store_short v132, v47, s[2:3] offset:64
	s_add_u32 s2, s18, 0x146400
	s_addc_u32 s3, s19, 0
	global_store_short v132, v64, s[2:3]
	global_store_short v132, v48, s[2:3] offset:64
	s_add_u32 s2, s18, 0x149e00
	s_addc_u32 s3, s19, 0
	global_store_short v132, v65, s[2:3]
	global_store_short v132, v49, s[2:3] offset:64
	s_add_u32 s2, s18, 0x15c000
	s_addc_u32 s3, s19, 0
	global_store_short v132, v18, s[2:3]
	global_store_short v132, v2, s[2:3] offset:64
	s_add_u32 s2, s18, 0x15fa00
	s_addc_u32 s3, s19, 0
	global_store_short v132, v19, s[2:3]
	global_store_short v132, v3, s[2:3] offset:64
	s_add_u32 s2, s18, 0x163400
	s_addc_u32 s3, s19, 0
	global_store_short v132, v20, s[2:3]
	global_store_short v132, v4, s[2:3] offset:64
	s_add_u32 s2, s18, 0x166e00
	s_addc_u32 s3, s19, 0
	global_store_short v132, v21, s[2:3]
	global_store_short v132, v5, s[2:3] offset:64
	s_add_u32 s2, s18, 0x179000
	s_addc_u32 s3, s19, 0
	global_store_short v132, v22, s[2:3]
	global_store_short v132, v6, s[2:3] offset:64
	s_add_u32 s2, s18, 0x17ca00
	s_addc_u32 s3, s19, 0
	global_store_short v132, v23, s[2:3]
	global_store_short v132, v7, s[2:3] offset:64
	s_add_u32 s2, s18, 0x180400
	s_addc_u32 s3, s19, 0
	global_store_short v132, v24, s[2:3]
	global_store_short v132, v8, s[2:3] offset:64
	s_add_u32 s2, s18, 0x183e00
	s_addc_u32 s3, s19, 0
	global_store_short v132, v25, s[2:3]
	global_store_short v132, v9, s[2:3] offset:64
	s_add_u32 s2, s18, 0x196000
	s_addc_u32 s3, s19, 0
	global_store_short v132, v26, s[2:3]
	global_store_short v132, v10, s[2:3] offset:64
	s_add_u32 s2, s18, 0x199a00
	s_addc_u32 s3, s19, 0
	global_store_short v132, v27, s[2:3]
	global_store_short v132, v11, s[2:3] offset:64
	s_add_u32 s2, s18, 0x19d400
	s_addc_u32 s3, s19, 0
	global_store_short v132, v28, s[2:3]
	global_store_short v132, v12, s[2:3] offset:64
	s_add_u32 s2, s18, 0x1a0e00
	s_addc_u32 s3, s19, 0
	global_store_short v132, v29, s[2:3]
	global_store_short v132, v13, s[2:3] offset:64
	s_add_u32 s2, s18, 0x1b3000
	s_addc_u32 s3, s19, 0
	global_store_short v132, v30, s[2:3]
	global_store_short v132, v14, s[2:3] offset:64
	s_add_u32 s2, s18, 0x1b6a00
	s_addc_u32 s3, s19, 0
	global_store_short v132, v31, s[2:3]
	global_store_short v132, v15, s[2:3] offset:64
	s_add_u32 s2, s18, 0x1ba400
	s_addc_u32 s3, s19, 0
	global_store_short v132, v32, s[2:3]
	global_store_short v132, v16, s[2:3] offset:64
	s_add_u32 s2, s18, 0x1bde00
	s_addc_u32 s3, s19, 0
	global_store_short v132, v33, s[2:3]
	global_store_short v132, v17, s[2:3] offset:64
	s_cmp_lg_u64 s[40:41], 0
	s_cbranch_scc0 .Lip_novt
; __device__ __forceinline__ void phase_inproj(const KP& p, int l, char* smem, int* q, int xcc) {
;     ...
;           if (vT) {
;             const int b = tok >> 13, t = tok & 8191;
;             vT[((size_t)(b * 2 + (col >> 6)) * 64 + (col & 63)) * SEQ + t] = hv;
;           }
	s_lshr_b32 s2, s14, 13
	s_lshl_b32 s2, s2, 21
	s_and_b32 s3, s14, 0x1fff
	s_lshl_b32 s3, s3, 1
	s_add_u32 s2, s2, s3
	s_add_u32 s40, s40, s2
	s_addc_u32 s41, s41, 0
	v_lshlrev_b32_e32 v135, 14, v134
	v_lshl_add_u32 v135, v130, 3, v135
	v_pack_b32_f16 v136, v114, v115
	v_pack_b32_f16 v137, v116, v117
	s_add_u32 s2, s40, 0x0
	s_addc_u32 s3, s41, 0
	global_store_dwordx2 v135, v[136:137], s[2:3]
	v_pack_b32_f16 v138, v118, v119
	v_pack_b32_f16 v139, v120, v121
	s_add_u32 s2, s40, 0x10
	s_addc_u32 s3, s41, 0
	global_store_dwordx2 v135, v[138:139], s[2:3]
	v_pack_b32_f16 v140, v122, v123
	v_pack_b32_f16 v141, v124, v125
	s_add_u32 s2, s40, 0x20
	s_addc_u32 s3, s41, 0
	global_store_dwordx2 v135, v[140:141], s[2:3]
	v_pack_b32_f16 v142, v126, v127
	v_pack_b32_f16 v143, v128, v129
	s_add_u32 s2, s40, 0x30
	s_addc_u32 s3, s41, 0
	global_store_dwordx2 v135, v[142:143], s[2:3]
	v_pack_b32_f16 v136, v98, v99
	v_pack_b32_f16 v137, v100, v101
	s_add_u32 s2, s40, 0x80000
	s_addc_u32 s3, s41, 0
	global_store_dwordx2 v135, v[136:137], s[2:3]
	v_pack_b32_f16 v138, v102, v103
	v_pack_b32_f16 v139, v104, v105
	s_add_u32 s2, s40, 0x80010
	s_addc_u32 s3, s41, 0
	global_store_dwordx2 v135, v[138:139], s[2:3]
	v_pack_b32_f16 v140, v106, v107
	v_pack_b32_f16 v141, v108, v109
	s_add_u32 s2, s40, 0x80020
	s_addc_u32 s3, s41, 0
	global_store_dwordx2 v135, v[140:141], s[2:3]
	v_pack_b32_f16 v142, v110, v111
	v_pack_b32_f16 v143, v112, v113
	s_add_u32 s2, s40, 0x80030
	s_addc_u32 s3, s41, 0
	global_store_dwordx2 v135, v[142:143], s[2:3]
	v_pack_b32_f16 v136, v82, v83
	v_pack_b32_f16 v137, v84, v85
	s_add_u32 s2, s40, 0x40
	s_addc_u32 s3, s41, 0
	global_store_dwordx2 v135, v[136:137], s[2:3]
	v_pack_b32_f16 v138, v86, v87
	v_pack_b32_f16 v139, v88, v89
	s_add_u32 s2, s40, 0x50
	s_addc_u32 s3, s41, 0
	global_store_dwordx2 v135, v[138:139], s[2:3]
	v_pack_b32_f16 v140, v90, v91
	v_pack_b32_f16 v141, v92, v93
	s_add_u32 s2, s40, 0x60
	s_addc_u32 s3, s41, 0
	global_store_dwordx2 v135, v[140:141], s[2:3]
	v_pack_b32_f16 v142, v94, v95
	v_pack_b32_f16 v143, v96, v97
	s_add_u32 s2, s40, 0x70
	s_addc_u32 s3, s41, 0
	global_store_dwordx2 v135, v[142:143], s[2:3]
	v_pack_b32_f16 v136, v66, v67
	v_pack_b32_f16 v137, v68, v69
	s_add_u32 s2, s40, 0x80040
	s_addc_u32 s3, s41, 0
	global_store_dwordx2 v135, v[136:137], s[2:3]
	v_pack_b32_f16 v138, v70, v71
	v_pack_b32_f16 v139, v72, v73
	s_add_u32 s2, s40, 0x80050
	s_addc_u32 s3, s41, 0
	global_store_dwordx2 v135, v[138:139], s[2:3]
	v_pack_b32_f16 v140, v74, v75
	v_pack_b32_f16 v141, v76, v77
	s_add_u32 s2, s40, 0x80060
	s_addc_u32 s3, s41, 0
	global_store_dwordx2 v135, v[140:141], s[2:3]
	v_pack_b32_f16 v142, v78, v79
	v_pack_b32_f16 v143, v80, v81
	s_add_u32 s2, s40, 0x80070
	s_addc_u32 s3, s41, 0
	global_store_dwordx2 v135, v[142:143], s[2:3]
	v_pack_b32_f16 v136, v50, v51
	v_pack_b32_f16 v137, v52, v53
	s_add_u32 s2, s40, 0x80
	s_addc_u32 s3, s41, 0
	global_store_dwordx2 v135, v[136:137], s[2:3]
	v_pack_b32_f16 v138, v54, v55
	v_pack_b32_f16 v139, v56, v57
	s_add_u32 s2, s40, 0x90
	s_addc_u32 s3, s41, 0
	global_store_dwordx2 v135, v[138:139], s[2:3]
	v_pack_b32_f16 v140, v58, v59
	v_pack_b32_f16 v141, v60, v61
	s_add_u32 s2, s40, 0xa0
	s_addc_u32 s3, s41, 0
	global_store_dwordx2 v135, v[140:141], s[2:3]
	v_pack_b32_f16 v142, v62, v63
	v_pack_b32_f16 v143, v64, v65
	s_add_u32 s2, s40, 0xb0
	s_addc_u32 s3, s41, 0
	global_store_dwordx2 v135, v[142:143], s[2:3]
	v_pack_b32_f16 v136, v34, v35
	v_pack_b32_f16 v137, v36, v37
	s_add_u32 s2, s40, 0x80080
	s_addc_u32 s3, s41, 0
	global_store_dwordx2 v135, v[136:137], s[2:3]
	v_pack_b32_f16 v138, v38, v39
	v_pack_b32_f16 v139, v40, v41
	s_add_u32 s2, s40, 0x80090
	s_addc_u32 s3, s41, 0
	global_store_dwordx2 v135, v[138:139], s[2:3]
	v_pack_b32_f16 v140, v42, v43
	v_pack_b32_f16 v141, v44, v45
	s_add_u32 s2, s40, 0x800a0
	s_addc_u32 s3, s41, 0
	global_store_dwordx2 v135, v[140:141], s[2:3]
	v_pack_b32_f16 v142, v46, v47
	v_pack_b32_f16 v143, v48, v49
	s_add_u32 s2, s40, 0x800b0
	s_addc_u32 s3, s41, 0
	global_store_dwordx2 v135, v[142:143], s[2:3]
	v_pack_b32_f16 v136, v18, v19
	v_pack_b32_f16 v137, v20, v21
	s_add_u32 s2, s40, 0xc0
	s_addc_u32 s3, s41, 0
	global_store_dwordx2 v135, v[136:137], s[2:3]
	v_pack_b32_f16 v138, v22, v23
	v_pack_b32_f16 v139, v24, v25
	s_add_u32 s2, s40, 0xd0
	s_addc_u32 s3, s41, 0
	global_store_dwordx2 v135, v[138:139], s[2:3]
	v_pack_b32_f16 v140, v26, v27
	v_pack_b32_f16 v141, v28, v29
	s_add_u32 s2, s40, 0xe0
	s_addc_u32 s3, s41, 0
	global_store_dwordx2 v135, v[140:141], s[2:3]
	v_pack_b32_f16 v142, v30, v31
	v_pack_b32_f16 v143, v32, v33
	s_add_u32 s2, s40, 0xf0
	s_addc_u32 s3, s41, 0
	global_store_dwordx2 v135, v[142:143], s[2:3]
	v_pack_b32_f16 v136, v2, v3
	v_pack_b32_f16 v137, v4, v5
	s_add_u32 s2, s40, 0x800c0
	s_addc_u32 s3, s41, 0
	global_store_dwordx2 v135, v[136:137], s[2:3]
	v_pack_b32_f16 v138, v6, v7
	v_pack_b32_f16 v139, v8, v9
	s_add_u32 s2, s40, 0x800d0
	s_addc_u32 s3, s41, 0
	global_store_dwordx2 v135, v[138:139], s[2:3]
	v_pack_b32_f16 v140, v10, v11
	v_pack_b32_f16 v141, v12, v13
	s_add_u32 s2, s40, 0x800e0
	s_addc_u32 s3, s41, 0
	global_store_dwordx2 v135, v[140:141], s[2:3]
	v_pack_b32_f16 v142, v14, v15
	v_pack_b32_f16 v143, v16, v17
	s_add_u32 s2, s40, 0x800f0
	s_addc_u32 s3, s41, 0
	global_store_dwordx2 v135, v[142:143], s[2:3]

;   __device__ __forceinline__ const float* x() const { return (const float*)(const __attribute__((address_space(1))) float*)kp[0]; }
;   __device__ __forceinline__ const float* ln_g() const { return (const float*)(const __attribute__((address_space(1))) float*)kp[16]; }
;   __device__ __forceinline__ const float* ln_b() const { return (const float*)(const __attribute__((address_space(1))) float*)kp[17]; }
;   __device__ __forceinline__ half_t* u() const { return (half_t*)(ws() + OFF_u); }
; __device__ __forceinline__ void ln_rows(const KP& p, int lprev, bool final_) {
;   int tid = threadIdx.x;
;   asm volatile("" : "+v"(tid));
;   const int lane = tid & 63, wid = tid >> 6;
;   const int gw = blockIdx.x * 4 + wid, nw = gridDim.x * 4;
;   for (int row = gw; row < NTOK; row += nw) {
;     const float4* rp = (const float4*)((lprev < 0 ? p.x() : (const float*)p.u()) + (size_t)row * DM);
;     float4 v[4];
;     float s = 0.f;
; #pragma unroll
;     for (int i = 0; i < 4; ++i) {
;       v[i] = rp[lane + 64 * i];
;       s += v[i].x + v[i].y + v[i].z + v[i].w;
;     }
;     if (lprev >= 0) {
;       float mu = wave_sum(s) * (1.f / DM);
;       float q = 0.f;
; #pragma unroll
;       for (int i = 0; i < 4; ++i) {
;         float a = v[i].x - mu, b = v[i].y - mu, c = v[i].z - mu, d = v[i].w - mu;
;         q += a * a + b * b + c * c + d * d;
;       }
;       float rstd = rsqrtf(wave_sum(q) * (1.f / DM) + 1e-5f);
;       const float4* g4 = (const float4*)(p.ln_g() + lprev * DM);
;       const float4* b4 = (const float4*)(p.ln_b() + lprev * DM);
.LBB0_1867:
	s_or_b64 exec, exec, s[0:1]
	v_readlane_b32 s0, v252, 31
	s_cmp_lg_u32 s0, 3
	s_cselect_b64 s[6:7], -1, 0
	v_readlane_b32 s10, v253, 1
	s_add_i32 s0, s0, 1
	v_readlane_b32 s11, v253, 2
	s_mov_b64 s[2:3], -1
	s_and_b64 vcc, exec, s[6:7]
	s_waitcnt lgkmcnt(0)
	s_barrier
	v_readlane_b32 s1, v252, 32
	s_cbranch_vccz .LBB0_1968
	v_mov_b32_e32 v0, v224
	v_readlane_b32 s1, v253, 3
	v_ashrrev_i32_e32 v2, 6, v0
	s_nop 0
	v_add_u32_e32 v2, s1, v2
	s_movk_i32 s1, 0x4000
	v_cmp_gt_i32_e32 vcc, s1, v2
	s_and_saveexec_b64 s[12:13], vcc
	s_cbranch_execz .LBB0_1871
	v_and_b32_e32 v10, 63, v0
	v_and_b32_e32 v77, 7, v10
	v_lshrrev_b32_e32 v78, 3, v10
	v_lshlrev_b32_e32 v77, 3, v77
	v_lshl_or_b32 v77, v78, 20, v77
	v_add_u32_e32 v77, 0x4000000, v77
	v_and_b32_e32 v0, 64, v237
	v_add_u32_e32 v0, 64, v0
	v_xor_b32_e32 v3, 32, v237
	v_cmp_lt_i32_e32 vcc, v3, v0
	s_load_dwordx4 s[40:43], s[10:11], 0x80
	s_load_dwordx2 s[16:17], s[10:11], 0x98
	v_cndmask_b32_e32 v3, v237, v3, vcc
	v_lshlrev_b32_e32 v12, 2, v3
	v_xor_b32_e32 v3, 16, v237
	v_cmp_lt_i32_e32 vcc, v3, v0
	v_readlane_b32 s2, v252, 31
	v_readlane_b32 s3, v252, 32
	v_cndmask_b32_e32 v3, v237, v3, vcc
	v_lshlrev_b32_e32 v13, 2, v3
	v_xor_b32_e32 v3, 8, v237
	v_cmp_lt_i32_e32 vcc, v3, v0
	s_lshl_b32 s8, s2, 10
	s_lshl_b64 s[2:3], s[8:9], 2
	v_cndmask_b32_e32 v3, v237, v3, vcc
	v_lshlrev_b32_e32 v14, 2, v3
	v_xor_b32_e32 v3, 4, v237
	v_cmp_lt_i32_e32 vcc, v3, v0
	s_waitcnt lgkmcnt(0)
	s_add_u32 s14, s40, s2
	s_addc_u32 s15, s41, s3
	v_cndmask_b32_e32 v3, v237, v3, vcc
	v_lshlrev_b32_e32 v15, 2, v3
	v_xor_b32_e32 v3, 2, v237
	v_cmp_lt_i32_e32 vcc, v3, v0
	s_add_u32 s2, s42, s2
	s_addc_u32 s3, s43, s3
	v_cndmask_b32_e32 v3, v237, v3, vcc
	v_lshlrev_b32_e32 v16, 2, v3
	v_xor_b32_e32 v3, 1, v237
	v_cmp_lt_i32_e32 vcc, v3, v0
	s_mov_b64 s[18:19], 0
	s_nop 0
	v_cndmask_b32_e32 v0, v237, v3, vcc
	v_ashrrev_i32_e32 v3, 31, v2
	v_lshlrev_b64 v[8:9], 11, v[2:3]
	v_lshlrev_b32_e32 v17, 2, v0
	v_lshlrev_b32_e32 v0, 4, v10
	v_lshl_or_b32 v8, v10, 3, v8
	v_lshlrev_b64 v[10:11], 12, v[2:3]
	v_lshl_add_u64 v[4:5], s[14:15], 0, v[0:1]
	v_lshl_add_u64 v[6:7], s[2:3], 0, v[0:1]
	v_or_b32_e32 v10, v10, v0
;   __device__ __forceinline__ const float* x() const { return (const float*)(const __attribute__((address_space(1))) float*)kp[0]; }
;   __device__ __forceinline__ const float* ln_g() const { return (const float*)(const __attribute__((address_space(1))) float*)kp[16]; }
;   __device__ __forceinline__ const float* ln_b() const { return (const float*)(const __attribute__((address_space(1))) float*)kp[17]; }
;   __device__ __forceinline__ float* out() const { return (float*)(__attribute__((address_space(1))) float*)kp[18]; }
; __device__ __forceinline__ void ln_rows(const KP& p, int lprev, bool final_) {
;     ...
;   for (int row = gw; row < NTOK; row += nw) {
;     const float4* rp = (const float4*)((lprev < 0 ? p.x() : (const float*)p.u()) + (size_t)row * DM);
;     float4 v[4];
;     float s = 0.f;
; #pragma unroll
;     for (int i = 0; i < 4; ++i) {
;       v[i] = rp[lane + 64 * i];
;       s += v[i].x + v[i].y + v[i].z + v[i].w;
;     }
;     if (lprev >= 0) {
;       float mu = wave_sum(s) * (1.f / DM);
;       float q = 0.f;
; #pragma unroll
;       for (int i = 0; i < 4; ++i) {
;         float a = v[i].x - mu, b = v[i].y - mu, c = v[i].z - mu, d = v[i].w - mu;
;         q += a * a + b * b + c * c + d * d;
;       }
;       float rstd = rsqrtf(wave_sum(q) * (1.f / DM) + 1e-5f);
;       const float4* g4 = (const float4*)(p.ln_g() + lprev * DM);
;       const float4* b4 = (const float4*)(p.ln_b() + lprev * DM);
; #pragma unroll
;       for (int i = 0; i < 4; ++i) {
;         float4 g = g4[lane + 64 * i], bb = b4[lane + 64 * i];
;         v[i].x = (v[i].x - mu) * rstd * g.x + bb.x;
;         v[i].y = (v[i].y - mu) * rstd * g.y + bb.y;
;         v[i].z = (v[i].z - mu) * rstd * g.z + bb.z;
;         v[i].w = (v[i].w - mu) * rstd * g.w + bb.w;
;       }
;     }
;     if (final_) {
;       float4* op = (float4*)(p.out() + (size_t)row * DM);
; #pragma unroll
;       for (int i = 0; i < 4; ++i) op[lane + 64 * i] = v[i];
;     } else {
;       float4* op = (float4*)(p.xr() + (size_t)row * DM);
;       h4* hp = (h4*)(p.xh() + (size_t)row * DM);
; #pragma unroll
;       for (int i = 0; i < 4; ++i) {
;         op[lane + 64 * i] = v[i];
;         h4 hv;
;         hv[0] = (half_t)v[i].x; hv[1] = (half_t)v[i].y; hv[2] = (half_t)v[i].z; hv[3] = (half_t)v[i].w;
;         hp[lane + 64 * i] = hv;
;       }
.LBB0_1870:
	v_lshl_add_u32 v76, v2, 6, v77
	v_lshl_add_u64 v[66:67], s[16:17], 0, v[10:11]
	v_add_co_u32_e32 v54, vcc, 0x6000000, v66
	v_lshl_add_u64 v[68:69], s[16:17], 0, v[8:9]
	s_nop 0
	v_addc_co_u32_e32 v55, vcc, 0, v67, vcc
	global_load_dwordx4 v[18:21], v[54:55], off
	global_load_dwordx4 v[22:25], v[4:5], off
	global_load_dwordx4 v[26:29], v[6:7], off
	global_load_dwordx4 v[30:33], v[54:55], off offset:1024
	global_load_dwordx4 v[34:37], v[4:5], off offset:1024
	global_load_dwordx4 v[38:41], v[6:7], off offset:1024
	v_add_u32_e32 v2, s48, v2
	v_lshl_add_u64 v[8:9], v[8:9], 0, s[70:71]
	v_lshl_add_u64 v[10:11], v[10:11], 0, s[78:79]
	s_waitcnt vmcnt(5)
	v_mov_b32_e32 v42, v18
	s_waitcnt vmcnt(2)
	v_mov_b32_e32 v43, v30
	v_mov_b32_e32 v44, v19
	v_mov_b32_e32 v45, v31
	v_pk_add_f32 v[42:43], v[42:43], v[44:45]
	v_mov_b32_e32 v44, v20
	v_mov_b32_e32 v45, v32
	v_pk_add_f32 v[42:43], v[42:43], v[44:45]
	v_mov_b32_e32 v44, v21
	v_mov_b32_e32 v45, v33
	v_pk_add_f32 v[42:43], v[42:43], v[44:45]
	s_nop 0
	v_add_f32_e32 v0, 0, v42
	v_add_f32_e32 v0, v0, v43
	global_load_dwordx4 v[42:45], v[54:55], off offset:2048
	global_load_dwordx4 v[46:49], v[4:5], off offset:2048
	global_load_dwordx4 v[50:53], v[6:7], off offset:2048
	s_nop 0
	global_load_dwordx4 v[54:57], v[54:55], off offset:3072
	s_nop 0
	global_load_dwordx4 v[58:61], v[4:5], off offset:3072
	global_load_dwordx4 v[62:65], v[6:7], off offset:3072
	s_waitcnt vmcnt(5)
	v_mov_b32_e32 v70, v42
	v_mov_b32_e32 v72, v43
	s_waitcnt vmcnt(2)
	v_mov_b32_e32 v71, v54
	v_mov_b32_e32 v73, v55
	v_pk_add_f32 v[70:71], v[70:71], v[72:73]
	v_mov_b32_e32 v72, v44
	v_mov_b32_e32 v73, v56
	v_pk_add_f32 v[70:71], v[70:71], v[72:73]
	v_mov_b32_e32 v72, v45
	v_mov_b32_e32 v73, v57
	v_pk_add_f32 v[70:71], v[70:71], v[72:73]
	s_nop 0
	v_add_f32_e32 v0, v0, v70
	v_add_f32_e32 v0, v0, v71
	ds_bpermute_b32 v3, v12, v0
	s_waitcnt lgkmcnt(0)
	v_add_f32_e32 v0, v0, v3
	ds_bpermute_b32 v3, v13, v0
	s_waitcnt lgkmcnt(0)
	v_add_f32_e32 v0, v0, v3
	ds_bpermute_b32 v3, v14, v0
	s_waitcnt lgkmcnt(0)
	v_add_f32_e32 v0, v0, v3
	ds_bpermute_b32 v3, v15, v0
	s_waitcnt lgkmcnt(0)
	v_add_f32_e32 v0, v0, v3
	ds_bpermute_b32 v3, v16, v0
	s_waitcnt lgkmcnt(0)
	v_add_f32_e32 v0, v0, v3
	ds_bpermute_b32 v3, v17, v0
	s_waitcnt lgkmcnt(0)
	v_add_f32_e32 v0, v0, v3
	v_mul_f32_e32 v0, 0x3a800000, v0
	v_pk_add_f32 v[18:19], v[18:19], v[0:1] op_sel_hi:[1,0] neg_lo:[0,1] neg_hi:[0,1]
	v_pk_add_f32 v[30:31], v[30:31], v[0:1] op_sel_hi:[1,0] neg_lo:[0,1] neg_hi:[0,1]
	v_mov_b32_e32 v72, v19
	v_mov_b32_e32 v73, v31
	v_pk_add_f32 v[20:21], v[20:21], v[0:1] op_sel_hi:[1,0] neg_lo:[0,1] neg_hi:[0,1]
	v_pk_add_f32 v[32:33], v[32:33], v[0:1] op_sel_hi:[1,0] neg_lo:[0,1] neg_hi:[0,1]
	v_mov_b32_e32 v70, v18
	v_mov_b32_e32 v71, v30
	v_pk_mul_f32 v[72:73], v[72:73], v[72:73]
	v_pk_add_f32 v[42:43], v[42:43], v[0:1] op_sel_hi:[1,0] neg_lo:[0,1] neg_hi:[0,1]
	v_pk_fma_f32 v[70:71], v[70:71], v[70:71], v[72:73]
	v_mov_b32_e32 v72, v20
	v_mov_b32_e32 v73, v32
	v_pk_add_f32 v[54:55], v[54:55], v[0:1] op_sel_hi:[1,0] neg_lo:[0,1] neg_hi:[0,1]
	v_pk_fma_f32 v[70:71], v[72:73], v[72:73], v[70:71]
	v_mov_b32_e32 v72, v21
	v_mov_b32_e32 v73, v33
	v_mov_b32_e32 v74, v55
	v_mov_b32_e32 v75, v43
	v_pk_fma_f32 v[70:71], v[72:73], v[72:73], v[70:71]
	v_pk_add_f32 v[44:45], v[44:45], v[0:1] op_sel_hi:[1,0] neg_lo:[0,1] neg_hi:[0,1]
	v_pk_add_f32 v[56:57], v[56:57], v[0:1] op_sel_hi:[1,0] neg_lo:[0,1] neg_hi:[0,1]
	v_mov_b32_e32 v72, v54
	v_mov_b32_e32 v73, v42
	v_pk_mul_f32 v[74:75], v[74:75], v[74:75]
	v_add_f32_e32 v0, v70, v71
	v_pk_fma_f32 v[72:73], v[72:73], v[72:73], v[74:75]
	v_mov_b32_e32 v74, v56
	v_mov_b32_e32 v75, v44
	v_pk_fma_f32 v[72:73], v[74:75], v[74:75], v[72:73]
	v_mov_b32_e32 v74, v57
	v_mov_b32_e32 v75, v45
	v_pk_fma_f32 v[72:73], v[74:75], v[74:75], v[72:73]
	s_nop 0
	v_add_f32_e32 v0, v73, v0
	v_add_f32_e32 v0, v72, v0
	ds_bpermute_b32 v3, v12, v0
	s_waitcnt lgkmcnt(0)
	v_add_f32_e32 v0, v0, v3
	ds_bpermute_b32 v3, v13, v0
	s_waitcnt lgkmcnt(0)
	v_add_f32_e32 v0, v0, v3
	ds_bpermute_b32 v3, v14, v0
	s_waitcnt lgkmcnt(0)
	v_add_f32_e32 v0, v0, v3
	ds_bpermute_b32 v3, v15, v0
	s_waitcnt lgkmcnt(0)
	v_add_f32_e32 v0, v0, v3
	ds_bpermute_b32 v3, v16, v0
	s_waitcnt lgkmcnt(0)
	v_add_f32_e32 v0, v0, v3
	ds_bpermute_b32 v3, v17, v0
	s_waitcnt lgkmcnt(0)
	v_add_f32_e32 v0, v0, v3
	v_fmamk_f32 v0, v0, 0x3a800000, v231
	v_cmp_gt_f32_e32 vcc, s66, v0
	v_mul_f32_e32 v3, 0x4b800000, v0
	s_nop 0
	v_cndmask_b32_e32 v0, v0, v3, vcc
	v_rsq_f32_e32 v0, v0
	s_nop 0
	v_mul_f32_e32 v3, 0x45800000, v0
	v_cndmask_b32_e32 v0, v0, v3, vcc
	v_pk_mul_f32 v[18:19], v[18:19], v[0:1] op_sel_hi:[1,0]
	v_pk_mul_f32 v[20:21], v[20:21], v[0:1] op_sel_hi:[1,0]
	v_pk_fma_f32 v[18:19], v[22:23], v[18:19], v[26:27]
	v_pk_fma_f32 v[20:21], v[24:25], v[20:21], v[28:29]
	v_pk_mul_f32 v[22:23], v[30:31], v[0:1] op_sel_hi:[1,0]
	v_pk_mul_f32 v[24:25], v[32:33], v[0:1] op_sel_hi:[1,0]
	global_store_dwordx4 v[66:67], v[18:21], off
	v_pk_fma_f32 v[22:23], v[34:35], v[22:23], v[38:39]
	v_pk_fma_f32 v[24:25], v[36:37], v[24:25], v[40:41]
	v_cvt_pk_f16_f32 v21, v20, v21
	v_cvt_pk_f16_f32 v20, v18, v19
	v_add_co_u32_e32 v18, vcc, s4, v68
	v_pk_mul_f32 v[26:27], v[42:43], v[0:1] op_sel_hi:[1,0]
	v_pk_mul_f32 v[28:29], v[44:45], v[0:1] op_sel_hi:[1,0]
	v_addc_co_u32_e32 v19, vcc, 0, v69, vcc
	v_pk_fma_f32 v[26:27], v[46:47], v[26:27], v[50:51]
	v_pk_fma_f32 v[28:29], v[28:29], v[48:49], v[52:53]
	v_pk_mul_f32 v[30:31], v[54:55], v[0:1] op_sel_hi:[1,0]
	v_pk_mul_f32 v[32:33], v[56:57], v[0:1] op_sel_hi:[1,0]
	global_store_dwordx2 v76, v[20:21], s[16:17]
	global_store_dwordx4 v[66:67], v[22:25], off offset:1024
	v_cvt_pk_f16_f32 v21, v24, v25
	v_cvt_pk_f16_f32 v20, v22, v23
	s_waitcnt vmcnt(3)
	v_pk_fma_f32 v[30:31], v[30:31], v[58:59], v[62:63]
	v_pk_fma_f32 v[32:33], v[32:33], v[60:61], v[64:65]
	v_add_u32_e32 v78, 0x800000, v76
	global_store_dwordx2 v78, v[20:21], s[16:17]
	global_store_dwordx4 v[66:67], v[26:29], off offset:2048
	v_cvt_pk_f16_f32 v21, v28, v29
	v_cvt_pk_f16_f32 v20, v26, v27
	v_cmp_lt_i32_e32 vcc, s67, v2
	v_add_u32_e32 v79, 0x1000000, v76
	global_store_dwordx2 v79, v[20:21], s[16:17]
	global_store_dwordx4 v[66:67], v[30:33], off offset:3072
	v_cvt_pk_f16_f32 v21, v32, v33
	v_cvt_pk_f16_f32 v20, v30, v31
	s_or_b64 s[18:19], vcc, s[18:19]
	v_add_u32_e32 v80, 0x1800000, v76
	global_store_dwordx2 v80, v[20:21], s[16:17]
	s_andn2_b64 exec, exec, s[18:19]
	s_cbranch_execnz .LBB0_1870

; template <class CM>
; __device__ __forceinline__ void tconv_tile(const float* __restrict__ src, int lds_, half_t* __restrict__ dst, int ldd,
;                                            int n0, int k0, CM cmap, char* smem) {
;     ...
;   __syncthreads();
; #pragma unroll
;   for (int i = 0; i < 2; ++i) {
;     const int idx = tid + 256 * i;
;     const int n = idx >> 3, kc = (idx & 7) * 8;
;     h8 v;
; #pragma unroll
;     for (int j = 0; j < 8; ++j) v[j] = (half_t)t[(kc + j) * 65 + n];
;     *(h8*)&dst[(size_t)(n0 + n) * ldd + k0 + kc] = v;
;   }
;   __syncthreads();
.LBB0_1873:
	s_or_b64 exec, exec, s[2:3]
	s_movk_i32 s2, 0x104
	v_and_b32_e32 v6, 63, v8
	v_mul_lo_u32 v7, v9, s2
	v_lshl_add_u32 v6, v6, 2, v7
	s_andn2_b32 s8, s8, 63
	s_waitcnt vmcnt(0)
	ds_write_b32 v6, v10
	ds_write_b32 v6, v0 offset:1040
	ds_write_b32 v6, v15 offset:2080
	ds_write_b32 v6, v14 offset:3120
	ds_write_b32 v6, v17 offset:4160
	ds_write_b32 v6, v16 offset:5200
	ds_write_b32 v6, v19 offset:6240
	ds_write_b32 v6, v18 offset:7280
	ds_write_b32 v6, v21 offset:8320
	ds_write_b32 v6, v20 offset:9360
	ds_write_b32 v6, v23 offset:10400
	ds_write_b32 v6, v22 offset:11440
	ds_write_b32 v6, v25 offset:12480
	ds_write_b32 v6, v24 offset:13520
	ds_write_b32 v6, v27 offset:14560
	ds_write_b32 v6, v26 offset:15600
	v_lshlrev_b32_e32 v0, 3, v8
	s_lshr_b32 s2, s14, 5
	s_mul_i32 s2, s2, 0x74000
	v_and_b32_e32 v9, 56, v0
	s_add_u32 s2, s42, s2
	s_addc_u32 s3, s43, 0
	v_lshrrev_b32_e32 v0, 5, v9
	v_and_b32_e32 v6, 31, v9
	v_mul_u32_u24_e32 v0, 0x74000, v0
	v_lshl_add_u32 v0, v6, 1, v0
	v_lshl_add_u64 v[6:7], s[2:3], 0, v[0:1]
	v_mul_u32_u24_e32 v0, 0x104, v9
	v_ashrrev_i32_e32 v9, 3, v8
	s_mov_b64 s[2:3], 0x14800000
	v_lshl_add_u32 v16, v9, 2, v0
	s_waitcnt lgkmcnt(0)
	s_barrier
	v_lshl_add_u64 v[10:11], v[6:7], 0, s[2:3]
	ds_read2_b32 v[6:7], v16 offset1:65
	ds_read2_b32 v[14:15], v16 offset0:130 offset1:195
	v_add_u32_e32 v16, 0x400, v16
	ds_read2_b32 v[18:19], v16 offset0:4 offset1:69
	ds_read2_b32 v[16:17], v16 offset0:134 offset1:199
	s_waitcnt lgkmcnt(2)
	v_cvt_pk_f16_f32 v15, v14, v15
	v_cvt_pk_f16_f32 v14, v6, v7
	v_add_u32_e32 v6, s8, v9
	v_ashrrev_i32_e32 v7, 31, v6
	v_lshlrev_b64 v[6:7], 6, v[6:7]
	s_waitcnt lgkmcnt(0)
	v_cvt_pk_f16_f32 v17, v16, v17
	v_cvt_pk_f16_f32 v16, v18, v19
	v_lshl_add_u64 v[6:7], v[10:11], 0, v[6:7]
	global_store_dwordx4 v[6:7], v[14:17], off
	v_add_u32_e32 v6, 0x100, v8
	v_ashrrev_i32_e32 v18, 3, v6
	v_lshl_add_u32 v0, v18, 2, v0
	ds_read2_b32 v[14:15], v0 offset1:65
	ds_read2_b32 v[6:7], v0 offset0:130 offset1:195
	v_add_u32_e32 v0, 0x400, v0
	ds_read2_b32 v[16:17], v0 offset0:4 offset1:69
	ds_read2_b32 v[8:9], v0 offset0:134 offset1:199
	s_waitcnt lgkmcnt(2)
	v_cvt_pk_f16_f32 v7, v6, v7
	v_cvt_pk_f16_f32 v6, v14, v15
	v_add_u32_e32 v14, s8, v18
	v_ashrrev_i32_e32 v15, 31, v14
	v_lshlrev_b64 v[14:15], 6, v[14:15]
	s_waitcnt lgkmcnt(0)
	v_cvt_pk_f16_f32 v9, v8, v9
	v_cvt_pk_f16_f32 v8, v16, v17
	v_lshl_add_u64 v[10:11], v[10:11], 0, v[14:15]
	global_store_dwordx4 v[10:11], v[6:9], off
	s_barrier
